# LRU gemm_tile: all 12 A/B tile loads issued up front with counted vmcnt (was load-wait-write serialized) + attn vmap/resched
# speedup vs baseline: 1.0948x; 1.0063x over previous
; #define MFMA16(a, b, c) __builtin_amdgcn_mfma_f32_16x16x32_bf16(a, b, c, 0, 0, 0)
; template <int EPI>
; __device__ __forceinline__ void gemm_tile(const Params& p, const EpiArgs& ea, const bf16_t* __restrict__ A, int lda,
;                                           const bf16_t* __restrict__ Bt, int K, int m0, int n0, char* smem) {
;     ...
;   const int srow = tid >> 3, sch = (tid & 7) * 8;
;   const bf16_t* ap = A + (size_t)(m0 + srow) * lda + sch;
;   const bf16_t* bp = Bt + (size_t)(n0 + srow) * K + sch;
;   const size_t a_step = (size_t)64 * lda, b_step = (size_t)64 * K;
;   uint4 ra[4], rb[2];
;   const int nk = K >> 6;
; #pragma unroll
;   for (int i = 0; i < 4; ++i) ra[i] = *(const uint4*)(ap + i * a_step);
; #pragma unroll
;   for (int i = 0; i < 2; ++i) rb[i] = *(const uint4*)(bp + i * b_step);
; #pragma unroll
;   for (int i = 0; i < 4; ++i) *(uint4*)(sA + (srow + i * 64) * LDT + sch) = ra[i];
; #pragma unroll
;   for (int i = 0; i < 2; ++i) *(uint4*)(sB + (srow + i * 64) * LDT + sch) = rb[i];
;   __syncthreads();
;   for (int kt = 0; kt < nk; ++kt) {
;     const int buf = kt & 1;
;     if (kt + 1 < nk) {
; #pragma unroll
;       for (int i = 0; i < 4; ++i) ra[i] = *(const uint4*)(ap + i * a_step + (kt + 1) * 64);
; #pragma unroll
;       for (int i = 0; i < 2; ++i) rb[i] = *(const uint4*)(bp + i * b_step + (kt + 1) * 64);
;     }
;     const bf16_t* cA = sA + buf * 256 * LDT + (wm * 64 + fr) * LDT + fq * 8;
;     const bf16_t* cB = sB + buf * 128 * LDT + (wn * 64 + fr) * LDT + fq * 8;
; #pragma unroll
;     for (int ks = 0; ks < 2; ++ks) {
;       bf16x8 af[4], bfg[4];
; #pragma unroll
;       for (int mi = 0; mi < 4; ++mi) af[mi] = *(const bf16x8*)(cA + mi * 16 * LDT + ks * 32);
; #pragma unroll
;       for (int ni = 0; ni < 4; ++ni) bfg[ni] = *(const bf16x8*)(cB + ni * 16 * LDT + ks * 32);
; #pragma unroll
;       for (int mi = 0; mi < 4; ++mi)
; #pragma unroll
;         for (int ni = 0; ni < 4; ++ni) acc[mi][ni] = MFMA16(af[mi], bfg[ni], acc[mi][ni]);
;     }
;     if (kt + 1 < nk) {
;       bf16_t* dA = sA + (buf ^ 1) * 256 * LDT;
;       bf16_t* dB = sB + (buf ^ 1) * 128 * LDT;
; #pragma unroll
;       for (int i = 0; i < 4; ++i) *(uint4*)(dA + (srow + i * 64) * LDT + sch) = ra[i];
; #pragma unroll
;       for (int i = 0; i < 2; ++i) *(uint4*)(dB + (srow + i * 64) * LDT + sch) = rb[i];
;     }
.LBB0_150:
	s_add_i32 s4, s7, s8
	s_cmpk_lt_i32 s4, 0x420
	s_mov_b64 s[2:3], -1
	s_cbranch_scc0 .LBB0_282
	s_ashr_i32 s2, s4, 31
	s_lshr_b32 s2, s2, 26
	s_add_i32 s2, s4, s2
	s_ashr_i32 s3, s2, 6
	s_lshl_b32 s5, s3, 2
	s_sub_i32 s5, 0x42, s5
	s_min_u32 s5, s5, 4
	v_cvt_f32_ubyte0_e32 v0, s5
	v_rcp_iflag_f32_e32 v0, v0
	s_andn2_b32 s2, s2, 63
	s_sub_i32 s9, s4, s2
	s_ashr_i32 s9, s9, 31
	v_mul_f32_e32 v0, 0x4f7ffffe, v0
	v_cvt_u32_f32_e32 v0, v0
	s_sub_i32 s10, 0, s5
	s_sub_i32 s2, s9, s2
	s_add_i32 s2, s4, s2
	v_readfirstlane_b32 s11, v0
	s_mul_i32 s10, s10, s11
	s_mul_hi_u32 s10, s11, s10
	s_xor_b32 s2, s2, s9
	s_add_i32 s11, s11, s10
	s_mul_hi_u32 s10, s2, s11
	s_mul_i32 s11, s10, s5
	s_sub_i32 s2, s2, s11
	s_add_i32 s11, s10, 1
	s_sub_i32 s12, s2, s5
	s_cmp_ge_u32 s2, s5
	s_cselect_b32 s10, s11, s10
	s_cselect_b32 s2, s12, s2
	s_add_i32 s11, s10, 1
	s_cmp_ge_u32 s2, s5
	s_cselect_b32 s2, s11, s10
	s_xor_b32 s2, s2, s9
	s_sub_i32 s9, s2, s9
	s_mul_i32 s2, s5, s9
	s_mul_i32 s3, s3, 60
	s_add_i32 s2, s2, s3
	s_sub_i32 s3, s4, s2
	s_lshl_b32 s2, s9, 6
	s_and_b32 s4, s2, 0xffffff80
	s_ashr_i32 s5, s4, 31
	s_lshl_b64 s[4:5], s[4:5], 1
	s_add_u32 s10, s40, s4
	v_mov_b32_e32 v65, v164
	s_addc_u32 s11, s41, s5
	s_lshl_b32 s4, s3, 8
	s_movk_i32 s5, 0x90
	v_ashrrev_i32_e32 v4, 3, v65
	v_add_u32_e32 v0, s4, v4
	v_ashrrev_i32_e32 v1, 31, v0
	v_lshlrev_b64 v[0:1], 11, v[0:1]
	v_lshlrev_b32_e32 v2, 4, v65
	v_lshl_add_u64 v[0:1], s[10:11], 0, v[0:1]
	v_and_b32_e32 v166, 0x70, v2
	v_lshl_add_u64 v[2:3], v[0:1], 0, v[166:167]
	v_lshl_add_u32 v0, s9, 7, v4
	s_waitcnt vmcnt(0)
	v_mul_lo_u32 v112, v4, s5
	global_load_dwordx4 v[120:123], v[2:3], off
	global_load_dwordx4 v[144:147], v[2:3], off offset:128
	v_add3_u32 v113, 0, v166, v112
	s_mov_b32 s3, 0x20000
	v_ashrrev_i32_e32 v1, 31, v0
	v_lshlrev_b64 v[0:1], 8, v[0:1]
	v_lshl_add_u64 v[0:1], s[44:45], 0, v[0:1]
	v_lshl_add_u64 v[0:1], v[0:1], 0, v[166:167]
	global_load_dwordx4 v[136:139], v[0:1], off
	global_load_dwordx4 v[148:151], v[0:1], off offset:128
	v_add_co_u32_e32 v4, vcc, s3, v2
	s_mov_b32 s3, 0x40000
	s_nop 0
	v_addc_co_u32_e32 v5, vcc, 0, v3, vcc
	global_load_dwordx4 v[124:127], v[4:5], off
	global_load_dwordx4 v[152:155], v[4:5], off offset:128
	v_add_co_u32_e32 v6, vcc, s3, v2
	s_mov_b32 s3, 0x60000
	s_nop 0
	v_addc_co_u32_e32 v7, vcc, 0, v3, vcc
	global_load_dwordx4 v[128:131], v[6:7], off
	global_load_dwordx4 v[156:159], v[6:7], off offset:128
	v_add_co_u32_e32 v8, vcc, s3, v2
	s_movk_i32 s3, 0x4000
	s_nop 0
	v_addc_co_u32_e32 v9, vcc, 0, v3, vcc
	global_load_dwordx4 v[132:135], v[8:9], off
	global_load_dwordx4 v[160:163], v[8:9], off offset:128
	v_add_co_u32_e32 v10, vcc, s3, v0
	v_readlane_b32 s3, v255, 30
	s_nop 0
	v_addc_co_u32_e32 v11, vcc, 0, v1, vcc
	global_load_dwordx4 v[140:143], v[10:11], off
	global_load_dwordx4 v[172:175], v[10:11], off offset:128
	v_readlane_b32 s9, v255, 29
	v_bfe_u32 v66, v65, 4, 2
	v_ashrrev_i32_e32 v64, 8, v65
	v_add3_u32 v16, s9, v166, v112
	v_and_b32_e32 v67, 15, v65
	s_waitcnt vmcnt(11)
	ds_write_b128 v113, v[120:123]
	s_waitcnt vmcnt(9)
	ds_write_b128 v16, v[136:139]
	s_waitcnt vmcnt(7)
	ds_write_b128 v113, v[124:127] offset:9216
	s_waitcnt vmcnt(5)
	ds_write_b128 v113, v[128:131] offset:18432
	s_waitcnt vmcnt(3)
	ds_write_b128 v113, v[132:135] offset:27648
	s_waitcnt vmcnt(1)
	ds_write_b128 v16, v[140:143] offset:9216
	v_and_b32_e32 v12, 0xcf, v65
	v_mul_u32_u24_e32 v12, 0x90, v12
	v_lshlrev_b32_e32 v13, 4, v66
	v_add3_u32 v114, 0, v12, v13
	v_lshl_or_b32 v12, v64, 6, v67
	v_mul_lo_u32 v12, v12, s5
	s_waitcnt lgkmcnt(0)
	s_barrier
	v_add3_u32 v116, s9, v12, v13
	ds_read_b128 v[12:15], v114
	ds_read_b128 v[16:19], v114 offset:2304
	ds_read_b128 v[20:23], v114 offset:4608
	ds_read_b128 v[24:27], v114 offset:6912
	ds_read_b128 v[28:31], v116
	ds_read_b128 v[32:35], v116 offset:2304
	ds_read_b128 v[36:39], v116 offset:4608
	ds_read_b128 v[40:43], v116 offset:6912
	s_waitcnt lgkmcnt(3)
	v_mfma_f32_16x16x32_bf16 v[44:47], v[12:15], v[28:31], 0
	v_or_b32_e32 v67, s2, v67
	v_lshl_add_u32 v64, v64, 5, v67
	s_mov_b32 s9, 0xbe99999a
	s_waitcnt lgkmcnt(2)
	v_mfma_f32_16x16x32_bf16 v[48:51], v[12:15], v[32:35], 0
	s_waitcnt lgkmcnt(1)
	v_mfma_f32_16x16x32_bf16 v[52:55], v[12:15], v[36:39], 0
	s_waitcnt lgkmcnt(0)
	v_mfma_f32_16x16x32_bf16 v[12:15], v[12:15], v[40:43], 0
	v_mfma_f32_16x16x32_bf16 v[56:59], v[16:19], v[28:31], 0
	v_mfma_f32_16x16x32_bf16 v[60:63], v[16:19], v[32:35], 0
	v_mfma_f32_16x16x32_bf16 v[68:71], v[16:19], v[36:39], 0
	v_mfma_f32_16x16x32_bf16 v[16:19], v[16:19], v[40:43], 0
	v_mfma_f32_16x16x32_bf16 v[72:75], v[20:23], v[28:31], 0
	v_mfma_f32_16x16x32_bf16 v[76:79], v[20:23], v[32:35], 0
	v_mfma_f32_16x16x32_bf16 v[80:83], v[20:23], v[36:39], 0
	v_mfma_f32_16x16x32_bf16 v[20:23], v[20:23], v[40:43], 0
	v_mfma_f32_16x16x32_bf16 v[28:31], v[24:27], v[28:31], 0
	v_mfma_f32_16x16x32_bf16 v[32:35], v[24:27], v[32:35], 0
	v_mfma_f32_16x16x32_bf16 v[36:39], v[24:27], v[36:39], 0
	v_mfma_f32_16x16x32_bf16 v[24:27], v[24:27], v[40:43], 0
	ds_read_b128 v[40:43], v114 offset:64
	ds_read_b128 v[84:87], v114 offset:2368
	ds_read_b128 v[88:91], v114 offset:4672
	ds_read_b128 v[92:95], v114 offset:6976
	ds_read_b128 v[96:99], v116 offset:64
	ds_read_b128 v[100:103], v116 offset:2368
	ds_read_b128 v[104:107], v116 offset:4672
	ds_read_b128 v[108:111], v116 offset:6976
	s_waitcnt lgkmcnt(3)
	v_mfma_f32_16x16x32_bf16 v[44:47], v[40:43], v[96:99], v[44:47]
	s_waitcnt lgkmcnt(2)
	v_mfma_f32_16x16x32_bf16 v[48:51], v[40:43], v[100:103], v[48:51]
	s_waitcnt lgkmcnt(1)
	v_mfma_f32_16x16x32_bf16 v[52:55], v[40:43], v[104:107], v[52:55]
	s_waitcnt lgkmcnt(0)
	v_mfma_f32_16x16x32_bf16 v[12:15], v[40:43], v[108:111], v[12:15]
	v_mfma_f32_16x16x32_bf16 v[40:43], v[84:87], v[96:99], v[56:59]
	v_mfma_f32_16x16x32_bf16 v[56:59], v[84:87], v[100:103], v[60:63]
	v_mfma_f32_16x16x32_bf16 v[60:63], v[84:87], v[104:107], v[68:71]
	v_mfma_f32_16x16x32_bf16 v[68:71], v[88:91], v[96:99], v[72:75]
	v_mfma_f32_16x16x32_bf16 v[72:75], v[88:91], v[100:103], v[76:79]
	v_mfma_f32_16x16x32_bf16 v[76:79], v[88:91], v[104:107], v[80:83]
	v_mfma_f32_16x16x32_bf16 v[16:19], v[84:87], v[108:111], v[16:19]
	v_add3_u32 v4, s3, v166, v112
	s_waitcnt vmcnt(0)
	ds_write_b128 v113, v[144:147] offset:36864
	v_mfma_f32_16x16x32_bf16 v[20:23], v[88:91], v[108:111], v[20:23]
	ds_write_b128 v4, v[148:151]
	ds_write_b128 v113, v[152:155] offset:46080
	v_mfma_f32_16x16x32_bf16 v[28:31], v[92:95], v[96:99], v[28:31]
	ds_write_b128 v113, v[156:159] offset:55296
	v_mfma_f32_16x16x32_bf16 v[32:35], v[92:95], v[100:103], v[32:35]
	ds_write_b128 v113, v[160:163] offset:64512
	v_mfma_f32_16x16x32_bf16 v[36:39], v[92:95], v[104:107], v[36:39]
	ds_write_b128 v4, v[172:175] offset:9216
	v_mfma_f32_16x16x32_bf16 v[24:27], v[92:95], v[108:111], v[24:27]
	s_waitcnt lgkmcnt(0)
	s_barrier
; #define MFMA16(a, b, c) __builtin_amdgcn_mfma_f32_16x16x32_bf16(a, b, c, 0, 0, 0)
; template <int EPI>
; __device__ __forceinline__ void gemm_tile(const Params& p, const EpiArgs& ea, const bf16_t* __restrict__ A, int lda,
;                                           const bf16_t* __restrict__ Bt, int K, int m0, int n0, char* smem) {
;     ...
;     const bf16_t* cA = sA + buf * 256 * LDT + (wm * 64 + fr) * LDT + fq * 8;
;     const bf16_t* cB = sB + buf * 128 * LDT + (wn * 64 + fr) * LDT + fq * 8;
; #pragma unroll
;     for (int ks = 0; ks < 2; ++ks) {
;       bf16x8 af[4], bfg[4];
; #pragma unroll
;       for (int mi = 0; mi < 4; ++mi) af[mi] = *(const bf16x8*)(cA + mi * 16 * LDT + ks * 32);
; #pragma unroll
;       for (int ni = 0; ni < 4; ++ni) bfg[ni] = *(const bf16x8*)(cB + ni * 16 * LDT + ks * 32);
; #pragma unroll
;       for (int mi = 0; mi < 4; ++mi)
; #pragma unroll
;         for (int ni = 0; ni < 4; ++ni) acc[mi][ni] = MFMA16(af[mi], bfg[ni], acc[mi][ni]);
;     }
;     ...
;     } else if (EPI == EPI_LRU) {
; #pragma unroll
;       for (int nh = 0; nh < 2; ++nh) {
;         int ch = (n0 >> 1) + wn * 32 + nh * 16 + fr;
;         float ba = p.lru_b_a[ea.dir * 1024 + ch], bx = p.lru_b_x[ea.dir * 1024 + ch];
;         float sp8 = -8.0f * log1pf(__expf(-p.lru_lam[ea.dir * 1024 + ch]));
	ds_read_b128 v[0:3], v114 offset:36864
	ds_read_b128 v[4:7], v114 offset:39168
	ds_read_b128 v[8:11], v114 offset:41472
	ds_read_b128 v[80:83], v114 offset:43776
	ds_read_b128 v[84:87], v116 offset:18432
	ds_read_b128 v[88:91], v116 offset:20736
	ds_read_b128 v[92:95], v116 offset:23040
	ds_read_b128 v[96:99], v116 offset:25344
	s_waitcnt lgkmcnt(3)
	v_mfma_f32_16x16x32_bf16 v[44:47], v[0:3], v[84:87], v[44:47]
	s_waitcnt lgkmcnt(2)
	v_mfma_f32_16x16x32_bf16 v[48:51], v[0:3], v[88:91], v[48:51]
	s_waitcnt lgkmcnt(1)
	v_mfma_f32_16x16x32_bf16 v[52:55], v[0:3], v[92:95], v[52:55]
	s_waitcnt lgkmcnt(0)
	v_mfma_f32_16x16x32_bf16 v[0:3], v[0:3], v[96:99], v[12:15]
	v_mfma_f32_16x16x32_bf16 v[12:15], v[4:7], v[84:87], v[40:43]
	v_mfma_f32_16x16x32_bf16 v[40:43], v[4:7], v[88:91], v[56:59]
	v_mfma_f32_16x16x32_bf16 v[100:103], v[4:7], v[92:95], v[60:63]
	v_mfma_f32_16x16x32_bf16 v[4:7], v[4:7], v[96:99], v[16:19]
	v_mfma_f32_16x16x32_bf16 v[16:19], v[8:11], v[84:87], v[68:71]
	v_mfma_f32_16x16x32_bf16 v[68:71], v[8:11], v[88:91], v[72:75]
	v_mfma_f32_16x16x32_bf16 v[72:75], v[8:11], v[92:95], v[76:79]
	v_mfma_f32_16x16x32_bf16 v[8:11], v[8:11], v[96:99], v[20:23]
	v_mfma_f32_16x16x32_bf16 v[76:79], v[80:83], v[84:87], v[28:31]
	v_mfma_f32_16x16x32_bf16 v[84:87], v[80:83], v[88:91], v[32:35]
	v_mfma_f32_16x16x32_bf16 v[88:91], v[80:83], v[92:95], v[36:39]
	v_mfma_f32_16x16x32_bf16 v[80:83], v[80:83], v[96:99], v[24:27]
	ds_read_b128 v[20:23], v114 offset:36928
	s_nop 1
	ds_read_b128 v[24:27], v114 offset:39232
	ds_read_b128 v[92:95], v114 offset:41536
	ds_read_b128 v[96:99], v114 offset:43840
	ds_read_b128 v[104:107], v116 offset:18496
	ds_read_b128 v[108:111], v116 offset:20800
	ds_read_b128 v[112:115], v116 offset:23104
	ds_read_b128 v[116:119], v116 offset:25408
	s_waitcnt lgkmcnt(0)
	s_barrier
	s_load_dwordx2 s[2:3], s[0:1], 0xc0
	s_load_dwordx4 s[12:15], s[0:1], 0xd0
	v_mfma_f32_16x16x32_bf16 v[60:63], v[20:23], v[104:107], v[44:47]
	v_mfma_f32_16x16x32_bf16 v[44:47], v[24:27], v[104:107], v[12:15]
	v_mfma_f32_16x16x32_bf16 v[40:43], v[24:27], v[108:111], v[40:43]
	v_mfma_f32_16x16x32_bf16 v[36:39], v[24:27], v[112:115], v[100:103]
	v_mfma_f32_16x16x32_bf16 v[32:35], v[24:27], v[116:119], v[4:7]
	v_mfma_f32_16x16x32_bf16 v[24:27], v[92:95], v[108:111], v[68:71]
	s_nop 2
	v_add_u32_e32 v68, s6, v64
	v_ashrrev_i32_e32 v69, 31, v68
	v_lshlrev_b64 v[68:69], 2, v[68:69]
	v_mfma_f32_16x16x32_bf16 v[56:59], v[20:23], v[108:111], v[48:51]
	v_mfma_f32_16x16x32_bf16 v[52:55], v[20:23], v[112:115], v[52:55]
	v_mfma_f32_16x16x32_bf16 v[48:51], v[20:23], v[116:119], v[0:3]
	v_mfma_f32_16x16x32_bf16 v[20:23], v[92:95], v[112:115], v[72:75]
	s_waitcnt lgkmcnt(0)
	s_nop 1
	v_lshl_add_u64 v[72:73], s[14:15], 0, v[68:69]
	global_load_dword v67, v[72:73], off
	v_lshl_add_u64 v[74:75], s[2:3], 0, v[68:69]
	v_mfma_f32_16x16x32_bf16 v[0:3], v[96:99], v[116:119], v[80:83]
	s_mov_b32 s2, 0x3f2aaaab
	s_waitcnt vmcnt(0)
	v_mul_f32_e32 v67, 0xbfb8aa3b, v67
	global_load_dword v83, v[74:75], off
	v_exp_f32_e32 v67, v67
	v_mfma_f32_16x16x32_bf16 v[12:15], v[96:99], v[104:107], v[76:79]
	v_add_f32_e32 v70, 1.0, v67
	s_nop 1
	v_lshl_add_u64 v[76:77], s[12:13], 0, v[68:69]
	v_add_f32_e32 v68, -1.0, v70
	global_load_dword v82, v[76:77], off
	v_sub_f32_e32 v69, v68, v70
	v_add_f32_e32 v69, 1.0, v69
	v_sub_f32_e32 v68, v67, v68
	v_add_f32_e32 v71, v68, v69
	v_frexp_mant_f32_e32 v68, v70
	v_cmp_gt_f32_e32 vcc, s2, v68
	v_cvt_f64_f32_e32 v[68:69], v70
	v_frexp_exp_i32_f64_e32 v68, v[68:69]
	v_mfma_f32_16x16x32_bf16 v[28:31], v[92:95], v[104:107], v[16:19]
	s_mov_b32 s2, 0x3f317218
	s_waitcnt vmcnt(1)
	v_add_f32_e32 v60, v60, v83
	v_mfma_f32_16x16x32_bf16 v[16:19], v[92:95], v[116:119], v[8:11]
	v_mul_f32_e32 v60, 0xbfb8aa3b, v60
	v_exp_f32_e32 v60, v60
	v_mfma_f32_16x16x32_bf16 v[8:11], v[96:99], v[108:111], v[84:87]
	v_add_f32_e32 v60, 1.0, v60
	v_rcp_f32_e32 v60, v60
	s_nop 0
	v_subbrev_co_u32_e32 v84, vcc, 0, v68, vcc
	v_sub_u32_e32 v68, 0, v84
	v_ldexp_f32 v69, v70, v68
	v_add_f32_e32 v70, -1.0, v69
	v_add_f32_e32 v78, 1.0, v69
	v_ldexp_f32 v68, v71, v68
	v_add_f32_e32 v71, 1.0, v70
	v_add_f32_e32 v79, -1.0, v78
	v_sub_f32_e32 v71, v69, v71
	v_sub_f32_e32 v69, v69, v79
	v_add_f32_e32 v71, v68, v71
	v_add_f32_e32 v68, v68, v69
	v_add_f32_e32 v85, v78, v68
	v_rcp_f32_e32 v87, v85
	v_sub_f32_e32 v69, v85, v78
	v_sub_f32_e32 v86, v68, v69
	v_add_f32_e32 v69, v70, v71
	v_mfma_f32_16x16x32_bf16 v[4:7], v[96:99], v[112:115], v[88:91]
	v_sub_f32_e32 v68, v69, v70
	s_nop 1
	v_mul_f32_e32 v89, v69, v87
	v_mul_f32_e32 v70, v85, v89
	v_fma_f32 v78, v89, v85, -v70
	v_fmac_f32_e32 v78, v89, v86
	v_sub_f32_e32 v88, v71, v68
	v_add_f32_e32 v68, v70, v78
	v_sub_f32_e32 v71, v69, v68
	v_pk_add_f32 v[80:81], v[68:69], v[70:71] neg_lo:[0,1] neg_hi:[0,1]
	v_mov_b32_e32 v79, v68
	v_pk_add_f32 v[68:69], v[80:81], v[78:79] neg_lo:[0,1] neg_hi:[0,1]
	s_nop 0
	v_add_f32_e32 v69, v88, v69
	v_add_f32_e32 v68, v68, v69
	v_add_f32_e32 v69, v71, v68
	v_mul_f32_e32 v88, v87, v69
	v_mul_f32_e32 v70, v85, v88
	v_fma_f32 v78, v88, v85, -v70
	v_fmac_f32_e32 v78, v88, v86
	v_sub_f32_e32 v71, v71, v69
	v_add_f32_e32 v85, v68, v71
	v_add_f32_e32 v68, v70, v78
	v_sub_f32_e32 v71, v69, v68
	v_pk_add_f32 v[80:81], v[68:69], v[70:71] neg_lo:[0,1] neg_hi:[0,1]
	v_mov_b32_e32 v79, v68
	v_pk_add_f32 v[68:69], v[80:81], v[78:79] neg_lo:[0,1] neg_hi:[0,1]
	s_nop 0
	v_add_f32_e32 v69, v85, v69
	v_add_f32_e32 v68, v68, v69
	v_add_f32_e32 v69, v89, v88
	v_add_f32_e32 v68, v71, v68
	v_sub_f32_e32 v70, v69, v89
	v_mul_f32_e32 v68, v87, v68
	v_sub_f32_e32 v70, v88, v70
	v_add_f32_e32 v70, v70, v68
	v_add_f32_e32 v78, v69, v70
;   __host__ __device__ __forceinline__ bf16_t* XC() const { return (bf16_t*)(wsl() + OFF_FFN); }
; __device__ __forceinline__ float bf2f(bf16_t h) { return __uint_as_float(((uint32_t)h) << 16); }
; __device__ __forceinline__ uint32_t pack2(float a, float b) { uint32_t r; asm("v_cvt_pk_bf16_f32 %0, %1, %2" : "=v"(r) : "v"(a), "v"(b)); return r; }
; __device__ __forceinline__ float sigmoidf_(float x) { return __builtin_amdgcn_rcpf(1.0f + __expf(-x)); }
; template <int EPI>
; __device__ __forceinline__ void gemm_tile(const Params& p, const EpiArgs& ea, const bf16_t* __restrict__ A, int lda,
;                                           const bf16_t* __restrict__ Bt, int K, int m0, int n0, char* smem) {
;     ...
;         float sp8 = -8.0f * log1pf(__expf(-p.lru_lam[ea.dir * 1024 + ch]));
; #pragma unroll
;         for (int j = 0; j < 4; ++j) {
;           float r = sigmoidf_(acc[mi][nh * 2][j] + ba);
;           float ig = sigmoidf_(acc[mi][nh * 2 + 1][j] + bx);
;           float la = r * sp8;
;           float x2 = 2.0f * la;
;           float poly = -x2 * (1.0f + x2 * (0.5f + x2 * (0.16666667f + x2 * (0.041666668f + x2 * (0.008333334f + x2 * 0.0013888889f)))));
;           float em = (x2 < -0.3f) ? (1.0f - __expf(x2)) : poly;
;           float u = bf2f(p.XC()[(size_t)(r0 + j) * D + ch]);
;           float inp = __builtin_amdgcn_sqrtf(fmaxf(em, 0.0f)) * (ig * u);
;           ea.outu[(size_t)(r0 + j) * D + ch] = pack2(la, inp);
	v_mul_f32_e32 v79, v78, v78
	v_fmamk_f32 v68, v79, 0x3e9b6dac, v165
	v_fmaak_f32 v171, v79, v68, 0x3f2aaada
	v_cvt_f32_i32_e32 v68, v84
	v_sub_f32_e32 v69, v78, v69
	v_sub_f32_e32 v69, v70, v69
	v_ldexp_f32 v80, v69, 1
	v_mul_f32_e32 v69, v78, v79
	v_ldexp_f32 v71, v78, 1
	v_pk_mul_f32 v[78:79], v[68:69], v[170:171]
	s_nop 0
	v_fma_f32 v70, v68, s2, -v78
	v_fmac_f32_e32 v70, 0xb102e308, v68
	v_pk_add_f32 v[68:69], v[78:79], v[70:71]
	s_mov_b32 s2, 0x7f800000
	v_sub_f32_e32 v71, v69, v71
	v_sub_f32_e32 v71, v79, v71
	v_add_f32_e32 v81, v80, v71
	v_mov_b32_e32 v80, v78
	v_pk_add_f32 v[78:79], v[68:69], v[78:79] neg_lo:[0,1] neg_hi:[0,1]
	v_pk_add_f32 v[84:85], v[68:69], v[80:81]
	v_mov_b32_e32 v71, v68
	v_mov_b32_e32 v79, v85
	v_pk_add_f32 v[86:87], v[70:71], v[78:79] neg_lo:[0,1] neg_hi:[0,1]
	v_pk_add_f32 v[70:71], v[70:71], v[78:79]
	v_mov_b32_e32 v80, v81
	v_pk_add_f32 v[78:79], v[70:71], v[68:69] op_sel:[1,0] op_sel_hi:[0,1] neg_lo:[0,1] neg_hi:[0,1]
	v_pk_add_f32 v[88:89], v[84:85], v[78:79] op_sel_hi:[1,0] neg_lo:[0,1] neg_hi:[0,1]
	v_mov_b32_e32 v84, v85
	v_mov_b32_e32 v85, v71
	v_pk_mov_b32 v[78:79], v[68:69], v[78:79] op_sel:[1,0]
	v_mov_b32_e32 v81, v68
	v_pk_add_f32 v[78:79], v[84:85], v[78:79] neg_lo:[0,1] neg_hi:[0,1]
	v_mov_b32_e32 v88, v86
	v_pk_add_f32 v[68:69], v[80:81], v[78:79] neg_lo:[0,1] neg_hi:[0,1]
	v_mov_b32_e32 v87, v71
	v_pk_add_f32 v[78:79], v[88:89], v[68:69]
	v_cmp_neq_f32_e32 vcc, s2, v67
	v_pk_add_f32 v[80:81], v[78:79], v[78:79] op_sel:[0,1] op_sel_hi:[1,0]
	s_mov_b32 s2, 0x33800000
	v_pk_add_f32 v[70:71], v[70:71], v[80:81] op_sel:[1,0] op_sel_hi:[0,1]
	v_mov_b32_e32 v79, v70
	v_pk_add_f32 v[84:85], v[78:79], v[86:87] neg_lo:[0,1] neg_hi:[0,1]
	v_mov_b32_e32 v69, v80
	v_sub_f32_e32 v71, v78, v84
	v_pk_add_f32 v[68:69], v[68:69], v[84:85] neg_lo:[0,1] neg_hi:[0,1]
	v_sub_f32_e32 v71, v86, v71
	v_add_f32_e32 v68, v68, v71
	v_add_f32_e32 v68, v68, v69
	v_add_f32_e32 v68, v70, v68
	v_cndmask_b32_e32 v68, v225, v68, vcc
	v_cmp_ngt_f32_e32 vcc, -1.0, v67
	s_nop 1
	v_cndmask_b32_e32 v68, v226, v68, vcc
	v_cmp_neq_f32_e32 vcc, -1.0, v67
	s_nop 1
	v_cndmask_b32_e32 v68, v227, v68, vcc
	v_cmp_lt_f32_e64 vcc, |v67|, s2
	s_nop 1
	v_cndmask_b32_e32 v67, v68, v67, vcc
	v_mul_f32_e32 v84, 0xc1000000, v67
	v_mul_f32_e32 v60, v60, v84
	v_add_f32_e32 v67, v60, v60
	v_cmp_ngt_f32_e32 vcc, s9, v67
	s_and_saveexec_b64 s[2:3], vcc
	s_xor_b64 s[2:3], exec, s[2:3]
	v_fmamk_f32 v68, v67, 0x3ab60b61, v169
	v_fmaak_f32 v68, v67, v68, 0x3d2aaaab
	v_fmaak_f32 v68, v67, v68, 0x3e2aaaab
	v_fma_f32 v68, v67, v68, 0.5
	v_fma_f32 v68, v67, v68, 1.0
	v_mul_f32_e64 v78, v68, -v67
	s_andn2_saveexec_b64 s[2:3], s[2:3]
	v_mul_f32_e32 v67, 0x3fb8aa3b, v67
	v_exp_f32_e32 v67, v67
	s_nop 0
	v_sub_f32_e32 v78, 1.0, v67
	s_or_b64 exec, exec, s[2:3]
	v_and_b32_e32 v65, 0xc0, v65
	v_lshlrev_b32_e32 v66, 2, v66
	v_or3_b32 v66, v66, v65, s4
	v_ashrrev_i32_e32 v67, 31, v66
	v_ashrrev_i32_e32 v65, 31, v64
	v_lshlrev_b64 v[68:69], 10, v[66:67]
	v_lshl_add_u64 v[80:81], v[68:69], 0, v[64:65]
	v_lshl_add_u64 v[70:71], v[80:81], 1, s[40:41]
	global_load_ushort v67, v[70:71], off
	s_waitcnt vmcnt(1)
	v_add_f32_e32 v56, v56, v82
	v_mul_f32_e32 v56, 0xbfb8aa3b, v56
	v_exp_f32_e32 v56, v56
	v_max_f32_e32 v78, v78, v78
	v_max_f32_e32 v78, 0, v78
	v_sqrt_f32_e32 v78, v78
	v_add_f32_e32 v56, 1.0, v56
	v_rcp_f32_e32 v56, v56
	s_waitcnt vmcnt(0)
	v_lshlrev_b32_e32 v67, 16, v67
	v_mul_f32_e32 v56, v56, v67
	v_mul_f32_e32 v56, v78, v56
	v_cvt_pk_bf16_f32 v56, v60, v56
	v_lshl_add_u64 v[78:79], v[80:81], 2, s[42:43]
	global_store_dword v[78:79], v56, off
	v_add_f32_e32 v56, v61, v83
	v_mul_f32_e32 v56, 0xbfb8aa3b, v56
	v_exp_f32_e32 v56, v56
	s_nop 0
	v_add_f32_e32 v56, 1.0, v56
	v_rcp_f32_e32 v56, v56
	s_nop 0
	v_mul_f32_e32 v67, v56, v84
	v_add_f32_e32 v56, v67, v67
	v_cmp_ngt_f32_e32 vcc, s9, v56
	s_and_saveexec_b64 s[2:3], vcc
	s_xor_b64 s[2:3], exec, s[2:3]
	v_fmamk_f32 v60, v56, 0x3ab60b61, v169
	v_fmaak_f32 v60, v56, v60, 0x3d2aaaab
	v_fmaak_f32 v60, v56, v60, 0x3e2aaaab
	v_fma_f32 v60, v56, v60, 0.5
	v_fma_f32 v60, v56, v60, 1.0
	v_mul_f32_e64 v78, v60, -v56
	s_andn2_saveexec_b64 s[2:3], s[2:3]
	v_mul_f32_e32 v56, 0x3fb8aa3b, v56
	v_exp_f32_e32 v56, v56
	s_nop 0
	v_sub_f32_e32 v78, 1.0, v56
	s_or_b64 exec, exec, s[2:3]
	v_add_f32_e32 v56, v57, v82
	v_mul_f32_e32 v56, 0xbfb8aa3b, v56
	v_exp_f32_e32 v56, v56
	v_add_f32_e32 v62, v62, v83
	v_mul_f32_e32 v62, 0xbfb8aa3b, v62
	v_exp_f32_e32 v62, v62
	v_add_f32_e32 v56, 1.0, v56
	v_rcp_f32_e32 v79, v56
	v_or_b32_e32 v56, 1, v66
	v_ashrrev_i32_e32 v57, 31, v56
	v_lshlrev_b64 v[56:57], 10, v[56:57]
	v_lshl_add_u64 v[80:81], v[56:57], 0, v[64:65]
	v_lshl_add_u64 v[60:61], v[80:81], 1, s[40:41]
	global_load_ushort v85, v[60:61], off
	v_max_f32_e32 v78, v78, v78
	v_max_f32_e32 v78, 0, v78
	v_sqrt_f32_e32 v78, v78
	v_add_f32_e32 v62, 1.0, v62
	v_rcp_f32_e32 v62, v62
	s_waitcnt vmcnt(0)
	v_lshlrev_b32_e32 v85, 16, v85
	v_mul_f32_e32 v79, v79, v85
	v_mul_f32_e32 v78, v78, v79
	v_cvt_pk_bf16_f32 v67, v67, v78
	v_lshl_add_u64 v[78:79], v[80:81], 2, s[42:43]
	v_mul_f32_e32 v62, v62, v84
	global_store_dword v[78:79], v67, off
	v_add_f32_e32 v67, v62, v62
	v_cmp_ngt_f32_e32 vcc, s9, v67
	s_and_saveexec_b64 s[2:3], vcc
	s_xor_b64 s[2:3], exec, s[2:3]
	v_fmamk_f32 v78, v67, 0x3ab60b61, v169
	v_fmaak_f32 v78, v67, v78, 0x3d2aaaab
	v_fmaak_f32 v78, v67, v78, 0x3e2aaaab
	v_fma_f32 v78, v67, v78, 0.5
	v_fma_f32 v78, v67, v78, 1.0
	v_mul_f32_e64 v85, v78, -v67
	s_andn2_saveexec_b64 s[2:3], s[2:3]
	v_mul_f32_e32 v67, 0x3fb8aa3b, v67
	v_exp_f32_e32 v67, v67
	s_nop 0
	v_sub_f32_e32 v85, 1.0, v67
	s_or_b64 exec, exec, s[2:3]
	v_or_b32_e32 v78, 2, v66
	v_ashrrev_i32_e32 v79, 31, v78
	v_lshlrev_b64 v[78:79], 10, v[78:79]
	v_lshl_add_u64 v[86:87], v[78:79], 0, v[64:65]
	v_lshl_add_u64 v[80:81], v[86:87], 1, s[40:41]
	global_load_ushort v88, v[80:81], off
	v_add_f32_e32 v63, v63, v83
	v_mul_f32_e32 v63, 0xbfb8aa3b, v63
	v_add_f32_e32 v58, v58, v82
	v_exp_f32_e32 v63, v63
	v_mul_f32_e32 v58, 0xbfb8aa3b, v58
	v_exp_f32_e32 v58, v58
	v_max_f32_e32 v67, v85, v85
	v_add_f32_e32 v63, 1.0, v63
	v_rcp_f32_e32 v63, v63
	v_add_f32_e32 v58, 1.0, v58
	v_max_f32_e32 v67, 0, v67
	v_rcp_f32_e32 v89, v58
	v_sqrt_f32_e32 v85, v67
	v_mul_f32_e32 v67, v63, v84
	v_add_f32_e32 v58, v67, v67
	v_lshl_add_u64 v[86:87], v[86:87], 2, s[42:43]
	v_cmp_ngt_f32_e32 vcc, s9, v58
	s_waitcnt vmcnt(0)
;   __host__ __device__ __forceinline__ bf16_t* XC() const { return (bf16_t*)(wsl() + OFF_FFN); }
; __device__ __forceinline__ float bf2f(bf16_t h) { return __uint_as_float(((uint32_t)h) << 16); }
; __device__ __forceinline__ uint32_t pack2(float a, float b) { uint32_t r; asm("v_cvt_pk_bf16_f32 %0, %1, %2" : "=v"(r) : "v"(a), "v"(b)); return r; }
; __device__ __forceinline__ float sigmoidf_(float x) { return __builtin_amdgcn_rcpf(1.0f + __expf(-x)); }
; template <int EPI>
; __device__ __forceinline__ void gemm_tile(const Params& p, const EpiArgs& ea, const bf16_t* __restrict__ A, int lda,
;                                           const bf16_t* __restrict__ Bt, int K, int m0, int n0, char* smem) {
;     ...
;         int ch = (n0 >> 1) + wn * 32 + nh * 16 + fr;
;         float ba = p.lru_b_a[ea.dir * 1024 + ch], bx = p.lru_b_x[ea.dir * 1024 + ch];
;         float sp8 = -8.0f * log1pf(__expf(-p.lru_lam[ea.dir * 1024 + ch]));
; #pragma unroll
;         for (int j = 0; j < 4; ++j) {
;           float r = sigmoidf_(acc[mi][nh * 2][j] + ba);
;           float ig = sigmoidf_(acc[mi][nh * 2 + 1][j] + bx);
;           float la = r * sp8;
;           float x2 = 2.0f * la;
;           float poly = -x2 * (1.0f + x2 * (0.5f + x2 * (0.16666667f + x2 * (0.041666668f + x2 * (0.008333334f + x2 * 0.0013888889f)))));
;           float em = (x2 < -0.3f) ? (1.0f - __expf(x2)) : poly;
;           float u = bf2f(p.XC()[(size_t)(r0 + j) * D + ch]);
;           float inp = __builtin_amdgcn_sqrtf(fmaxf(em, 0.0f)) * (ig * u);
;           ea.outu[(size_t)(r0 + j) * D + ch] = pack2(la, inp);
	v_lshlrev_b32_e32 v63, 16, v88
	v_mul_f32_e32 v63, v89, v63
	v_mul_f32_e32 v63, v85, v63
	v_cvt_pk_bf16_f32 v62, v62, v63
	global_store_dword v[86:87], v62, off
	s_and_saveexec_b64 s[2:3], vcc
	s_xor_b64 s[2:3], exec, s[2:3]
	v_fmamk_f32 v62, v58, 0x3ab60b61, v169
	v_fmaak_f32 v62, v58, v62, 0x3d2aaaab
	v_fmaak_f32 v62, v58, v62, 0x3e2aaaab
	v_fma_f32 v62, v58, v62, 0.5
	v_fma_f32 v62, v58, v62, 1.0
	v_mul_f32_e64 v85, v62, -v58
	s_andn2_saveexec_b64 s[2:3], s[2:3]
	v_mul_f32_e32 v58, 0x3fb8aa3b, v58
	v_exp_f32_e32 v58, v58
	s_nop 0
	v_sub_f32_e32 v85, 1.0, v58
	s_or_b64 exec, exec, s[2:3]
	v_add_f32_e32 v58, v59, v82
	v_mul_f32_e32 v58, 0xbfb8aa3b, v58
	v_exp_f32_e32 v58, v58
	v_max_f32_e32 v85, v85, v85
	v_max_f32_e32 v85, 0, v85
	v_sqrt_f32_e32 v85, v85
	v_add_f32_e32 v58, 1.0, v58
	v_rcp_f32_e32 v88, v58
	v_or_b32_e32 v58, 3, v66
	v_ashrrev_i32_e32 v59, 31, v58
	v_lshlrev_b64 v[58:59], 10, v[58:59]
	v_lshl_add_u64 v[86:87], v[58:59], 0, v[64:65]
	v_lshl_add_u64 v[62:63], v[86:87], 1, s[40:41]
	global_load_ushort v89, v[62:63], off
	v_lshl_add_u64 v[86:87], v[86:87], 2, s[42:43]
	s_mov_b32 s2, 0x3f2aaaab
	s_waitcnt vmcnt(0)
	v_lshlrev_b32_e32 v89, 16, v89
	v_mul_f32_e32 v88, v88, v89
	v_mul_f32_e32 v85, v85, v88
	v_cvt_pk_bf16_f32 v67, v67, v85
	global_store_dword v[86:87], v67, off
	global_load_dword v74, v[74:75], off offset:64
	s_nop 0
	global_load_dword v67, v[76:77], off offset:64
	s_nop 0
	global_load_dword v72, v[72:73], off offset:64
	s_waitcnt vmcnt(2)
	v_add_f32_e32 v52, v52, v74
	v_mul_f32_e32 v52, 0xbfb8aa3b, v52
	s_waitcnt vmcnt(0)
	v_mul_f32_e32 v72, 0xbfb8aa3b, v72
	v_exp_f32_e32 v75, v72
	v_exp_f32_e32 v52, v52
	v_add_f32_e32 v76, 1.0, v75
	v_add_f32_e32 v72, -1.0, v76
	v_sub_f32_e32 v73, v72, v76
	v_add_f32_e32 v73, 1.0, v73
	v_sub_f32_e32 v72, v75, v72
	v_add_f32_e32 v77, v72, v73
	v_frexp_mant_f32_e32 v72, v76
	v_cmp_gt_f32_e32 vcc, s2, v72
	v_cvt_f64_f32_e32 v[72:73], v76
	v_frexp_exp_i32_f64_e32 v72, v[72:73]
	v_subbrev_co_u32_e32 v85, vcc, 0, v72, vcc
	v_sub_u32_e32 v72, 0, v85
	v_ldexp_f32 v73, v76, v72
	v_add_f32_e32 v76, -1.0, v73
	v_add_f32_e32 v86, 1.0, v73
	v_ldexp_f32 v72, v77, v72
	v_add_f32_e32 v77, 1.0, v76
	v_add_f32_e32 v87, -1.0, v86
	v_sub_f32_e32 v77, v73, v77
	v_sub_f32_e32 v73, v73, v87
	v_add_f32_e32 v77, v72, v77
	v_add_f32_e32 v72, v72, v73
	v_add_f32_e32 v90, v86, v72
	v_rcp_f32_e32 v92, v90
	v_sub_f32_e32 v73, v90, v86
	v_sub_f32_e32 v91, v72, v73
	v_add_f32_e32 v73, v76, v77
	v_mul_f32_e32 v94, v73, v92
	v_sub_f32_e32 v72, v73, v76
	v_mul_f32_e32 v76, v90, v94
	v_fma_f32 v86, v94, v90, -v76
	v_fmac_f32_e32 v86, v94, v91
	v_sub_f32_e32 v93, v77, v72
	v_add_f32_e32 v72, v76, v86
	v_sub_f32_e32 v77, v73, v72
	v_pk_add_f32 v[88:89], v[72:73], v[76:77] neg_lo:[0,1] neg_hi:[0,1]
	v_mov_b32_e32 v87, v72
	v_pk_add_f32 v[72:73], v[88:89], v[86:87] neg_lo:[0,1] neg_hi:[0,1]
	s_mov_b32 s2, 0x3f317218
	v_add_f32_e32 v73, v93, v73
	v_add_f32_e32 v72, v72, v73
	v_add_f32_e32 v73, v77, v72
	v_mul_f32_e32 v93, v92, v73
	v_mul_f32_e32 v76, v90, v93
	v_fma_f32 v86, v93, v90, -v76
	v_fmac_f32_e32 v86, v93, v91
	v_sub_f32_e32 v77, v77, v73
	v_add_f32_e32 v90, v72, v77
	v_add_f32_e32 v72, v76, v86
	v_sub_f32_e32 v77, v73, v72
	v_pk_add_f32 v[88:89], v[72:73], v[76:77] neg_lo:[0,1] neg_hi:[0,1]
	v_mov_b32_e32 v87, v72
	v_pk_add_f32 v[72:73], v[88:89], v[86:87] neg_lo:[0,1] neg_hi:[0,1]
	v_add_f32_e32 v52, 1.0, v52
	v_add_f32_e32 v73, v90, v73
	v_add_f32_e32 v72, v72, v73
	v_add_f32_e32 v73, v94, v93
	v_add_f32_e32 v72, v77, v72
	v_sub_f32_e32 v76, v73, v94
	v_mul_f32_e32 v72, v92, v72
	v_sub_f32_e32 v76, v93, v76
	v_add_f32_e32 v76, v76, v72
	v_add_f32_e32 v86, v73, v76
	v_mul_f32_e32 v87, v86, v86
	v_fmamk_f32 v72, v87, 0x3e9b6dac, v165
	v_fmaak_f32 v171, v87, v72, 0x3f2aaada
	v_cvt_f32_i32_e32 v72, v85
	v_sub_f32_e32 v73, v86, v73
	v_sub_f32_e32 v73, v76, v73
	v_ldexp_f32 v85, v73, 1
	v_mul_f32_e32 v73, v86, v87
	v_ldexp_f32 v77, v86, 1
	v_pk_mul_f32 v[86:87], v[72:73], v[170:171]
	v_rcp_f32_e32 v52, v52
	v_fma_f32 v76, v72, s2, -v86
	v_fmac_f32_e32 v76, 0xb102e308, v72
	v_pk_add_f32 v[72:73], v[86:87], v[76:77]
	v_mov_b32_e32 v88, v86
	v_sub_f32_e32 v77, v73, v77
	v_sub_f32_e32 v77, v87, v77
	v_add_f32_e32 v89, v85, v77
	v_pk_add_f32 v[86:87], v[72:73], v[86:87] neg_lo:[0,1] neg_hi:[0,1]
	v_pk_add_f32 v[90:91], v[72:73], v[88:89]
	v_mov_b32_e32 v77, v72
	v_mov_b32_e32 v87, v91
	v_pk_add_f32 v[92:93], v[76:77], v[86:87] neg_lo:[0,1] neg_hi:[0,1]
	v_pk_add_f32 v[76:77], v[76:77], v[86:87]
	v_mov_b32_e32 v88, v89
	v_pk_add_f32 v[86:87], v[76:77], v[72:73] op_sel:[1,0] op_sel_hi:[0,1] neg_lo:[0,1] neg_hi:[0,1]
	v_pk_add_f32 v[94:95], v[90:91], v[86:87] op_sel_hi:[1,0] neg_lo:[0,1] neg_hi:[0,1]
	v_mov_b32_e32 v90, v91
	v_mov_b32_e32 v91, v77
	v_pk_mov_b32 v[86:87], v[72:73], v[86:87] op_sel:[1,0]
	v_mov_b32_e32 v89, v72
	v_pk_add_f32 v[86:87], v[90:91], v[86:87] neg_lo:[0,1] neg_hi:[0,1]
	v_mov_b32_e32 v94, v92
	v_pk_add_f32 v[72:73], v[88:89], v[86:87] neg_lo:[0,1] neg_hi:[0,1]
	v_mov_b32_e32 v93, v77
	v_pk_add_f32 v[86:87], v[94:95], v[72:73]
	s_mov_b32 s2, 0x7f800000
	v_pk_add_f32 v[88:89], v[86:87], v[86:87] op_sel:[0,1] op_sel_hi:[1,0]
	v_cmp_neq_f32_e32 vcc, s2, v75
	v_pk_add_f32 v[76:77], v[76:77], v[88:89] op_sel:[1,0] op_sel_hi:[0,1]
	v_mov_b32_e32 v87, v76
	v_pk_add_f32 v[90:91], v[86:87], v[92:93] neg_lo:[0,1] neg_hi:[0,1]
	v_mov_b32_e32 v73, v88
	v_sub_f32_e32 v77, v86, v90
	v_pk_add_f32 v[72:73], v[72:73], v[90:91] neg_lo:[0,1] neg_hi:[0,1]
	v_sub_f32_e32 v77, v92, v77
	v_add_f32_e32 v72, v72, v77
	v_add_f32_e32 v72, v72, v73
	v_add_f32_e32 v72, v76, v72
	v_cndmask_b32_e32 v72, v225, v72, vcc
;   __host__ __device__ __forceinline__ bf16_t* XC() const { return (bf16_t*)(wsl() + OFF_FFN); }
; __device__ __forceinline__ float bf2f(bf16_t h) { return __uint_as_float(((uint32_t)h) << 16); }
; __device__ __forceinline__ uint32_t pack2(float a, float b) { uint32_t r; asm("v_cvt_pk_bf16_f32 %0, %1, %2" : "=v"(r) : "v"(a), "v"(b)); return r; }
; __device__ __forceinline__ float sigmoidf_(float x) { return __builtin_amdgcn_rcpf(1.0f + __expf(-x)); }
; template <int EPI>
; __device__ __forceinline__ void gemm_tile(const Params& p, const EpiArgs& ea, const bf16_t* __restrict__ A, int lda,
;                                           const bf16_t* __restrict__ Bt, int K, int m0, int n0, char* smem) {
;     ...
;         for (int j = 0; j < 4; ++j) {
;           float r = sigmoidf_(acc[mi][nh * 2][j] + ba);
;           float ig = sigmoidf_(acc[mi][nh * 2 + 1][j] + bx);
;           float la = r * sp8;
;           float x2 = 2.0f * la;
;           float poly = -x2 * (1.0f + x2 * (0.5f + x2 * (0.16666667f + x2 * (0.041666668f + x2 * (0.008333334f + x2 * 0.0013888889f)))));
;           float em = (x2 < -0.3f) ? (1.0f - __expf(x2)) : poly;
;           float u = bf2f(p.XC()[(size_t)(r0 + j) * D + ch]);
;           float inp = __builtin_amdgcn_sqrtf(fmaxf(em, 0.0f)) * (ig * u);
;           ea.outu[(size_t)(r0 + j) * D + ch] = pack2(la, inp);
	v_cmp_ngt_f32_e32 vcc, -1.0, v75
	s_mov_b32 s2, 0x33800000
	s_nop 0
	v_cndmask_b32_e32 v72, v226, v72, vcc
	v_cmp_neq_f32_e32 vcc, -1.0, v75
	s_nop 1
	v_cndmask_b32_e32 v72, v227, v72, vcc
	v_cmp_lt_f32_e64 vcc, |v75|, s2
	s_nop 1
	v_cndmask_b32_e32 v72, v72, v75, vcc
	v_mul_f32_e32 v72, 0xc1000000, v72
	v_mul_f32_e32 v73, v52, v72
	v_add_f32_e32 v52, v73, v73
	v_cmp_ngt_f32_e32 vcc, s9, v52
	s_and_saveexec_b64 s[2:3], vcc
	s_xor_b64 s[2:3], exec, s[2:3]
	v_fmamk_f32 v75, v52, 0x3ab60b61, v169
	v_fmaak_f32 v75, v52, v75, 0x3d2aaaab
	v_fmaak_f32 v75, v52, v75, 0x3e2aaaab
	v_fma_f32 v75, v52, v75, 0.5
	v_fma_f32 v75, v52, v75, 1.0
	v_mul_f32_e64 v75, v75, -v52
	s_andn2_saveexec_b64 s[2:3], s[2:3]
	v_mul_f32_e32 v52, 0x3fb8aa3b, v52
	v_exp_f32_e32 v52, v52
	s_nop 0
	v_sub_f32_e32 v75, 1.0, v52
	s_or_b64 exec, exec, s[2:3]
	global_load_ushort v76, v[70:71], off offset:32
	v_add_f32_e32 v48, v48, v67
	v_add_f32_e32 v71, v53, v74
	v_mul_f32_e32 v48, 0xbfb8aa3b, v48
	v_mul_f32_e32 v71, 0xbfb8aa3b, v71
	v_exp_f32_e32 v71, v71
	v_exp_f32_e32 v48, v48
	v_or_b32_e32 v52, 16, v64
	v_max_f32_e32 v70, v75, v75
	v_ashrrev_i32_e32 v53, 31, v52
	v_max_f32_e32 v70, 0, v70
	v_lshl_add_u64 v[68:69], v[68:69], 0, v[52:53]
	v_sqrt_f32_e32 v75, v70
	v_add_f32_e32 v70, 1.0, v71
	v_add_f32_e32 v48, 1.0, v48
	v_rcp_f32_e32 v77, v70
	v_lshl_add_u64 v[70:71], v[68:69], 2, s[42:43]
	v_rcp_f32_e32 v68, v48
	v_mul_f32_e32 v48, v77, v72
	v_add_f32_e32 v69, v48, v48
	v_cmp_ngt_f32_e32 vcc, s9, v69
	s_waitcnt vmcnt(0)
	v_lshlrev_b32_e32 v76, 16, v76
	v_mul_f32_e32 v68, v68, v76
	v_mul_f32_e32 v68, v75, v68
	v_cvt_pk_bf16_f32 v68, v73, v68
	global_store_dword v[70:71], v68, off
	s_and_saveexec_b64 s[2:3], vcc
	s_xor_b64 s[2:3], exec, s[2:3]
	v_fmamk_f32 v68, v69, 0x3ab60b61, v169
	v_fmaak_f32 v68, v69, v68, 0x3d2aaaab
	v_fmaak_f32 v68, v69, v68, 0x3e2aaaab
	v_fma_f32 v68, v69, v68, 0.5
	v_fma_f32 v68, v69, v68, 1.0
	v_mul_f32_e64 v68, v68, -v69
	s_andn2_saveexec_b64 s[2:3], s[2:3]
	v_mul_f32_e32 v68, 0x3fb8aa3b, v69
	v_exp_f32_e32 v68, v68
	s_nop 0
	v_sub_f32_e32 v68, 1.0, v68
	s_or_b64 exec, exec, s[2:3]
	global_load_ushort v60, v[60:61], off offset:32
	v_add_f32_e32 v54, v54, v74
	v_add_f32_e32 v49, v49, v67
	v_mul_f32_e32 v54, 0xbfb8aa3b, v54
	v_mul_f32_e32 v49, 0xbfb8aa3b, v49
	v_exp_f32_e32 v54, v54
	v_exp_f32_e32 v49, v49
	v_max_f32_e32 v61, v68, v68
	v_max_f32_e32 v61, 0, v61
	v_add_f32_e32 v54, 1.0, v54
	v_rcp_f32_e32 v54, v54
	v_add_f32_e32 v49, 1.0, v49
	v_rcp_f32_e32 v68, v49
	v_sqrt_f32_e32 v61, v61
	v_mul_f32_e32 v49, v54, v72
	v_lshl_add_u64 v[56:57], v[56:57], 0, v[52:53]
	v_add_f32_e32 v54, v49, v49
	v_lshl_add_u64 v[56:57], v[56:57], 2, s[42:43]
	v_cmp_ngt_f32_e32 vcc, s9, v54
	s_waitcnt vmcnt(0)
	v_lshlrev_b32_e32 v60, 16, v60
	v_mul_f32_e32 v60, v68, v60
	v_mul_f32_e32 v60, v61, v60
	v_cvt_pk_bf16_f32 v48, v48, v60
	global_store_dword v[56:57], v48, off
	s_and_saveexec_b64 s[2:3], vcc
	s_xor_b64 s[2:3], exec, s[2:3]
	v_fmamk_f32 v48, v54, 0x3ab60b61, v169
	v_fmaak_f32 v48, v54, v48, 0x3d2aaaab
	v_fmaak_f32 v48, v54, v48, 0x3e2aaaab
	v_fma_f32 v48, v54, v48, 0.5
	v_fma_f32 v48, v54, v48, 1.0
	v_mul_f32_e64 v48, v48, -v54
	s_andn2_saveexec_b64 s[2:3], s[2:3]
	v_mul_f32_e32 v48, 0x3fb8aa3b, v54
	v_exp_f32_e32 v48, v48
	s_nop 0
	v_sub_f32_e32 v48, 1.0, v48
	s_or_b64 exec, exec, s[2:3]
	global_load_ushort v60, v[80:81], off offset:32
	v_add_f32_e32 v54, v55, v74
	v_add_f32_e32 v50, v50, v67
	v_mul_f32_e32 v54, 0xbfb8aa3b, v54
	v_mul_f32_e32 v50, 0xbfb8aa3b, v50
	v_exp_f32_e32 v61, v54
	v_exp_f32_e32 v50, v50
	v_lshl_add_u64 v[56:57], v[78:79], 0, v[52:53]
	v_max_f32_e32 v48, v48, v48
	v_max_f32_e32 v48, 0, v48
	v_lshl_add_u64 v[54:55], v[56:57], 2, s[42:43]
	v_add_f32_e32 v56, 1.0, v61
	v_rcp_f32_e32 v56, v56
	v_sqrt_f32_e32 v57, v48
	v_add_f32_e32 v48, 1.0, v50
	v_rcp_f32_e32 v61, v48
	v_mul_f32_e32 v48, v56, v72
	v_add_f32_e32 v50, v48, v48
	v_cmp_ngt_f32_e32 vcc, s9, v50
	s_waitcnt vmcnt(0)
	v_lshlrev_b32_e32 v56, 16, v60
	v_mul_f32_e32 v56, v61, v56
	v_mul_f32_e32 v56, v57, v56
	v_cvt_pk_bf16_f32 v49, v49, v56
	global_store_dword v[54:55], v49, off
	s_and_saveexec_b64 s[2:3], vcc
	s_xor_b64 s[2:3], exec, s[2:3]
	v_fmamk_f32 v49, v50, 0x3ab60b61, v169
	v_fmaak_f32 v49, v50, v49, 0x3d2aaaab
	v_fmaak_f32 v49, v50, v49, 0x3e2aaaab
	v_fma_f32 v49, v50, v49, 0.5
	v_fma_f32 v49, v50, v49, 1.0
	v_mul_f32_e64 v49, v49, -v50
	s_andn2_saveexec_b64 s[2:3], s[2:3]
	v_mul_f32_e32 v49, 0x3fb8aa3b, v50
	v_exp_f32_e32 v49, v49
	s_nop 0
	v_sub_f32_e32 v49, 1.0, v49
	s_or_b64 exec, exec, s[2:3]
	global_load_ushort v54, v[62:63], off offset:32
	v_add_f32_e32 v44, v44, v83
	v_add_f32_e32 v55, v51, v67
	v_mul_f32_e32 v44, 0xbfb8aa3b, v44
	v_mul_f32_e32 v55, 0xbfb8aa3b, v55
	v_exp_f32_e32 v44, v44
	v_exp_f32_e32 v55, v55
	v_max_f32_e32 v49, v49, v49
	v_max_f32_e32 v49, 0, v49
	v_add_f32_e32 v44, 1.0, v44
	v_rcp_f32_e32 v44, v44
	v_sqrt_f32_e32 v56, v49
	v_add_f32_e32 v49, 1.0, v55
	v_rcp_f32_e32 v55, v49
	v_mul_f32_e32 v44, v44, v84
	v_lshl_add_u64 v[50:51], v[58:59], 0, v[52:53]
	v_add_f32_e32 v49, v44, v44
	v_lshl_add_u64 v[50:51], v[50:51], 2, s[42:43]
	v_cmp_ngt_f32_e32 vcc, s9, v49
	s_waitcnt vmcnt(0)
;   __host__ __device__ __forceinline__ bf16_t* XC() const { return (bf16_t*)(wsl() + OFF_FFN); }
; __device__ __forceinline__ float bf2f(bf16_t h) { return __uint_as_float(((uint32_t)h) << 16); }
; __device__ __forceinline__ uint32_t pack2(float a, float b) { uint32_t r; asm("v_cvt_pk_bf16_f32 %0, %1, %2" : "=v"(r) : "v"(a), "v"(b)); return r; }
; __device__ __forceinline__ float sigmoidf_(float x) { return __builtin_amdgcn_rcpf(1.0f + __expf(-x)); }
; template <int EPI>
; __device__ __forceinline__ void gemm_tile(const Params& p, const EpiArgs& ea, const bf16_t* __restrict__ A, int lda,
;                                           const bf16_t* __restrict__ Bt, int K, int m0, int n0, char* smem) {
;     ...
;         for (int j = 0; j < 4; ++j) {
;           float r = sigmoidf_(acc[mi][nh * 2][j] + ba);
;           float ig = sigmoidf_(acc[mi][nh * 2 + 1][j] + bx);
;           float la = r * sp8;
;           float x2 = 2.0f * la;
;           float poly = -x2 * (1.0f + x2 * (0.5f + x2 * (0.16666667f + x2 * (0.041666668f + x2 * (0.008333334f + x2 * 0.0013888889f)))));
;           float em = (x2 < -0.3f) ? (1.0f - __expf(x2)) : poly;
;           float u = bf2f(p.XC()[(size_t)(r0 + j) * D + ch]);
;           float inp = __builtin_amdgcn_sqrtf(fmaxf(em, 0.0f)) * (ig * u);
;           ea.outu[(size_t)(r0 + j) * D + ch] = pack2(la, inp);
	v_lshlrev_b32_e32 v54, 16, v54
	v_mul_f32_e32 v54, v55, v54
	v_mul_f32_e32 v54, v56, v54
	v_cvt_pk_bf16_f32 v48, v48, v54
	global_store_dword v[50:51], v48, off
	s_and_saveexec_b64 s[2:3], vcc
	s_xor_b64 s[2:3], exec, s[2:3]
	v_fmamk_f32 v48, v49, 0x3ab60b61, v169
	v_fmaak_f32 v48, v49, v48, 0x3d2aaaab
	v_fmaak_f32 v48, v49, v48, 0x3e2aaaab
	v_fma_f32 v48, v49, v48, 0.5
	v_fma_f32 v48, v49, v48, 1.0
	v_mul_f32_e64 v54, v48, -v49
	s_andn2_saveexec_b64 s[2:3], s[2:3]
	v_mul_f32_e32 v48, 0x3fb8aa3b, v49
	v_exp_f32_e32 v48, v48
	s_nop 0
	v_sub_f32_e32 v54, 1.0, v48
	s_or_b64 exec, exec, s[2:3]
	v_or_b32_e32 v48, 16, v66
	v_ashrrev_i32_e32 v49, 31, v48
	v_lshlrev_b64 v[48:49], 10, v[48:49]
	v_lshl_add_u64 v[56:57], v[48:49], 0, v[64:65]
	v_lshl_add_u64 v[50:51], v[56:57], 1, s[40:41]
	global_load_ushort v55, v[50:51], off
	v_add_f32_e32 v40, v40, v82
	v_mul_f32_e32 v40, 0xbfb8aa3b, v40
	v_exp_f32_e32 v40, v40
	v_max_f32_e32 v54, v54, v54
	v_max_f32_e32 v54, 0, v54
	v_sqrt_f32_e32 v54, v54
	v_add_f32_e32 v40, 1.0, v40
	v_rcp_f32_e32 v40, v40
	s_waitcnt vmcnt(0)
	v_lshlrev_b32_e32 v55, 16, v55
	v_mul_f32_e32 v40, v40, v55
	v_mul_f32_e32 v40, v54, v40
	v_cvt_pk_bf16_f32 v40, v44, v40
	v_lshl_add_u64 v[54:55], v[56:57], 2, s[42:43]
	global_store_dword v[54:55], v40, off
	v_add_f32_e32 v40, v45, v83
	v_mul_f32_e32 v40, 0xbfb8aa3b, v40
	v_exp_f32_e32 v40, v40
	s_nop 0
	v_add_f32_e32 v40, 1.0, v40
	v_rcp_f32_e32 v40, v40
	s_nop 0
	v_mul_f32_e32 v54, v40, v84
	v_add_f32_e32 v40, v54, v54
	v_cmp_ngt_f32_e32 vcc, s9, v40
	s_and_saveexec_b64 s[2:3], vcc
	s_xor_b64 s[2:3], exec, s[2:3]
	v_fmamk_f32 v44, v40, 0x3ab60b61, v169
	v_fmaak_f32 v44, v40, v44, 0x3d2aaaab
	v_fmaak_f32 v44, v40, v44, 0x3e2aaaab
	v_fma_f32 v44, v40, v44, 0.5
	v_fma_f32 v44, v40, v44, 1.0
	v_mul_f32_e64 v55, v44, -v40
	s_andn2_saveexec_b64 s[2:3], s[2:3]
	v_mul_f32_e32 v40, 0x3fb8aa3b, v40
	v_exp_f32_e32 v40, v40
	s_nop 0
	v_sub_f32_e32 v55, 1.0, v40
	s_or_b64 exec, exec, s[2:3]
	v_add_f32_e32 v40, v41, v82
	v_mul_f32_e32 v40, 0xbfb8aa3b, v40
	v_exp_f32_e32 v40, v40
	v_add_f32_e32 v46, v46, v83
	v_mul_f32_e32 v46, 0xbfb8aa3b, v46
	v_exp_f32_e32 v46, v46
	v_add_f32_e32 v40, 1.0, v40
	v_rcp_f32_e32 v58, v40
	v_or_b32_e32 v40, 17, v66
	v_ashrrev_i32_e32 v41, 31, v40
	v_lshlrev_b64 v[40:41], 10, v[40:41]
	v_lshl_add_u64 v[56:57], v[40:41], 0, v[64:65]
	v_lshl_add_u64 v[44:45], v[56:57], 1, s[40:41]
	global_load_ushort v59, v[44:45], off
	v_max_f32_e32 v55, v55, v55
	v_max_f32_e32 v55, 0, v55
	v_sqrt_f32_e32 v55, v55
	v_add_f32_e32 v46, 1.0, v46
	v_rcp_f32_e32 v46, v46
	s_waitcnt vmcnt(0)
	v_lshlrev_b32_e32 v59, 16, v59
	v_mul_f32_e32 v58, v58, v59
	v_mul_f32_e32 v55, v55, v58
	v_cvt_pk_bf16_f32 v58, v54, v55
	v_lshl_add_u64 v[54:55], v[56:57], 2, s[42:43]
	v_mul_f32_e32 v46, v46, v84
	global_store_dword v[54:55], v58, off
	v_add_f32_e32 v54, v46, v46
	v_cmp_ngt_f32_e32 vcc, s9, v54
	s_and_saveexec_b64 s[2:3], vcc
	s_xor_b64 s[2:3], exec, s[2:3]
	v_fmamk_f32 v55, v54, 0x3ab60b61, v169
	v_fmaak_f32 v55, v54, v55, 0x3d2aaaab
	v_fmaak_f32 v55, v54, v55, 0x3e2aaaab
	v_fma_f32 v55, v54, v55, 0.5
	v_fma_f32 v55, v54, v55, 1.0
	v_mul_f32_e64 v58, v55, -v54
	s_andn2_saveexec_b64 s[2:3], s[2:3]
	v_mul_f32_e32 v54, 0x3fb8aa3b, v54
	v_exp_f32_e32 v54, v54
	s_nop 0
	v_sub_f32_e32 v58, 1.0, v54
	s_or_b64 exec, exec, s[2:3]
	v_or_b32_e32 v54, 18, v66
	v_ashrrev_i32_e32 v55, 31, v54
	v_lshlrev_b64 v[54:55], 10, v[54:55]
	v_lshl_add_u64 v[60:61], v[54:55], 0, v[64:65]
	v_lshl_add_u64 v[56:57], v[60:61], 1, s[40:41]
	global_load_ushort v59, v[56:57], off
	v_add_f32_e32 v47, v47, v83
	v_mul_f32_e32 v47, 0xbfb8aa3b, v47
	v_add_f32_e32 v42, v42, v82
	v_exp_f32_e32 v47, v47
	v_mul_f32_e32 v42, 0xbfb8aa3b, v42
	v_exp_f32_e32 v42, v42
	v_max_f32_e32 v58, v58, v58
	v_add_f32_e32 v47, 1.0, v47
	v_rcp_f32_e32 v47, v47
	v_add_f32_e32 v42, 1.0, v42
	v_max_f32_e32 v58, 0, v58
	v_rcp_f32_e32 v63, v42
	v_sqrt_f32_e32 v62, v58
	v_mul_f32_e32 v58, v47, v84
	v_add_f32_e32 v42, v58, v58
	v_lshl_add_u64 v[60:61], v[60:61], 2, s[42:43]
	v_cmp_ngt_f32_e32 vcc, s9, v42
	s_waitcnt vmcnt(0)
	v_lshlrev_b32_e32 v47, 16, v59
	v_mul_f32_e32 v47, v63, v47
	v_mul_f32_e32 v47, v62, v47
	v_cvt_pk_bf16_f32 v46, v46, v47
	global_store_dword v[60:61], v46, off
	s_and_saveexec_b64 s[2:3], vcc
	s_xor_b64 s[2:3], exec, s[2:3]
	v_fmamk_f32 v46, v42, 0x3ab60b61, v169
	v_fmaak_f32 v46, v42, v46, 0x3d2aaaab
	v_fmaak_f32 v46, v42, v46, 0x3e2aaaab
	v_fma_f32 v46, v42, v46, 0.5
	v_fma_f32 v46, v42, v46, 1.0
	v_mul_f32_e64 v59, v46, -v42
	s_andn2_saveexec_b64 s[2:3], s[2:3]
	v_mul_f32_e32 v42, 0x3fb8aa3b, v42
	v_exp_f32_e32 v42, v42
	s_nop 0
	v_sub_f32_e32 v59, 1.0, v42
	s_or_b64 exec, exec, s[2:3]
	v_add_f32_e32 v42, v43, v82
	v_mul_f32_e32 v42, 0xbfb8aa3b, v42
	v_exp_f32_e32 v42, v42
	v_add_f32_e32 v36, v36, v74
	v_mul_f32_e32 v36, 0xbfb8aa3b, v36
	v_exp_f32_e32 v36, v36
	v_add_f32_e32 v42, 1.0, v42
	v_rcp_f32_e32 v62, v42
	v_or_b32_e32 v42, 19, v66
	v_ashrrev_i32_e32 v43, 31, v42
	v_lshlrev_b64 v[42:43], 10, v[42:43]
	v_lshl_add_u64 v[60:61], v[42:43], 0, v[64:65]
	v_lshl_add_u64 v[46:47], v[60:61], 1, s[40:41]
	global_load_ushort v63, v[46:47], off
	v_max_f32_e32 v59, v59, v59
	v_max_f32_e32 v59, 0, v59
	v_sqrt_f32_e32 v59, v59
	v_add_f32_e32 v36, 1.0, v36
	v_rcp_f32_e32 v36, v36
	s_waitcnt vmcnt(0)
;   __host__ __device__ __forceinline__ bf16_t* XC() const { return (bf16_t*)(wsl() + OFF_FFN); }
; __device__ __forceinline__ float bf2f(bf16_t h) { return __uint_as_float(((uint32_t)h) << 16); }
; __device__ __forceinline__ uint32_t pack2(float a, float b) { uint32_t r; asm("v_cvt_pk_bf16_f32 %0, %1, %2" : "=v"(r) : "v"(a), "v"(b)); return r; }
; __device__ __forceinline__ float sigmoidf_(float x) { return __builtin_amdgcn_rcpf(1.0f + __expf(-x)); }
; template <int EPI>
; __device__ __forceinline__ void gemm_tile(const Params& p, const EpiArgs& ea, const bf16_t* __restrict__ A, int lda,
;                                           const bf16_t* __restrict__ Bt, int K, int m0, int n0, char* smem) {
;     ...
;         for (int j = 0; j < 4; ++j) {
;           float r = sigmoidf_(acc[mi][nh * 2][j] + ba);
;           float ig = sigmoidf_(acc[mi][nh * 2 + 1][j] + bx);
;           float la = r * sp8;
;           float x2 = 2.0f * la;
;           float poly = -x2 * (1.0f + x2 * (0.5f + x2 * (0.16666667f + x2 * (0.041666668f + x2 * (0.008333334f + x2 * 0.0013888889f)))));
;           float em = (x2 < -0.3f) ? (1.0f - __expf(x2)) : poly;
;           float u = bf2f(p.XC()[(size_t)(r0 + j) * D + ch]);
;           float inp = __builtin_amdgcn_sqrtf(fmaxf(em, 0.0f)) * (ig * u);
;           ea.outu[(size_t)(r0 + j) * D + ch] = pack2(la, inp);
	v_lshlrev_b32_e32 v63, 16, v63
	v_mul_f32_e32 v62, v62, v63
	v_mul_f32_e32 v59, v59, v62
	v_cvt_pk_bf16_f32 v62, v58, v59
	v_lshl_add_u64 v[58:59], v[60:61], 2, s[42:43]
	v_mul_f32_e32 v36, v36, v72
	global_store_dword v[58:59], v62, off
	v_add_f32_e32 v58, v36, v36
	v_cmp_ngt_f32_e32 vcc, s9, v58
	s_and_saveexec_b64 s[2:3], vcc
	s_xor_b64 s[2:3], exec, s[2:3]
	v_fmamk_f32 v59, v58, 0x3ab60b61, v169
	v_fmaak_f32 v59, v58, v59, 0x3d2aaaab
	v_fmaak_f32 v59, v58, v59, 0x3e2aaaab
	v_fma_f32 v59, v58, v59, 0.5
	v_fma_f32 v59, v58, v59, 1.0
	v_mul_f32_e64 v59, v59, -v58
	s_andn2_saveexec_b64 s[2:3], s[2:3]
	v_mul_f32_e32 v58, 0x3fb8aa3b, v58
	v_exp_f32_e32 v58, v58
	s_nop 0
	v_sub_f32_e32 v59, 1.0, v58
	s_or_b64 exec, exec, s[2:3]
	global_load_ushort v50, v[50:51], off offset:32
	v_add_f32_e32 v37, v37, v74
	v_add_f32_e32 v32, v32, v67
	v_mul_f32_e32 v37, 0xbfb8aa3b, v37
	v_mul_f32_e32 v32, 0xbfb8aa3b, v32
	v_exp_f32_e32 v37, v37
	v_exp_f32_e32 v32, v32
	v_max_f32_e32 v51, v59, v59
	v_max_f32_e32 v51, 0, v51
	v_add_f32_e32 v37, 1.0, v37
	v_rcp_f32_e32 v37, v37
	v_add_f32_e32 v32, 1.0, v32
	v_rcp_f32_e32 v58, v32
	v_sqrt_f32_e32 v51, v51
	v_mul_f32_e32 v32, v37, v72
	v_lshl_add_u64 v[48:49], v[48:49], 0, v[52:53]
	v_add_f32_e32 v37, v32, v32
	v_lshl_add_u64 v[48:49], v[48:49], 2, s[42:43]
	v_cmp_ngt_f32_e32 vcc, s9, v37
	s_waitcnt vmcnt(0)
	v_lshlrev_b32_e32 v50, 16, v50
	v_mul_f32_e32 v50, v58, v50
	v_mul_f32_e32 v50, v51, v50
	v_cvt_pk_bf16_f32 v36, v36, v50
	global_store_dword v[48:49], v36, off
	s_and_saveexec_b64 s[2:3], vcc
	s_xor_b64 s[2:3], exec, s[2:3]
	v_fmamk_f32 v36, v37, 0x3ab60b61, v169
	v_fmaak_f32 v36, v37, v36, 0x3d2aaaab
	v_fmaak_f32 v36, v37, v36, 0x3e2aaaab
	v_fma_f32 v36, v37, v36, 0.5
	v_fma_f32 v36, v37, v36, 1.0
	v_mul_f32_e64 v36, v36, -v37
	s_andn2_saveexec_b64 s[2:3], s[2:3]
	v_mul_f32_e32 v36, 0x3fb8aa3b, v37
	v_exp_f32_e32 v36, v36
	s_nop 0
	v_sub_f32_e32 v36, 1.0, v36
	s_or_b64 exec, exec, s[2:3]
	global_load_ushort v37, v[44:45], off offset:32
	v_add_f32_e32 v38, v38, v74
	v_add_f32_e32 v33, v33, v67
	v_mul_f32_e32 v38, 0xbfb8aa3b, v38
	v_mul_f32_e32 v33, 0xbfb8aa3b, v33
	v_exp_f32_e32 v38, v38
	v_exp_f32_e32 v33, v33
	v_max_f32_e32 v36, v36, v36
	v_max_f32_e32 v36, 0, v36
	v_add_f32_e32 v38, 1.0, v38
	v_rcp_f32_e32 v38, v38
	v_add_f32_e32 v33, 1.0, v33
	v_rcp_f32_e32 v45, v33
	v_sqrt_f32_e32 v44, v36
	v_mul_f32_e32 v33, v38, v72
	v_lshl_add_u64 v[40:41], v[40:41], 0, v[52:53]
	v_add_f32_e32 v36, v33, v33
	v_lshl_add_u64 v[40:41], v[40:41], 2, s[42:43]
	v_cmp_ngt_f32_e32 vcc, s9, v36
	s_waitcnt vmcnt(0)
	v_lshlrev_b32_e32 v37, 16, v37
	v_mul_f32_e32 v37, v45, v37
	v_mul_f32_e32 v37, v44, v37
	v_cvt_pk_bf16_f32 v32, v32, v37
	global_store_dword v[40:41], v32, off
	s_and_saveexec_b64 s[2:3], vcc
	s_xor_b64 s[2:3], exec, s[2:3]
	v_fmamk_f32 v32, v36, 0x3ab60b61, v169
	v_fmaak_f32 v32, v36, v32, 0x3d2aaaab
	v_fmaak_f32 v32, v36, v32, 0x3e2aaaab
	v_fma_f32 v32, v36, v32, 0.5
	v_fma_f32 v32, v36, v32, 1.0
	v_mul_f32_e64 v32, v32, -v36
	s_andn2_saveexec_b64 s[2:3], s[2:3]
	v_mul_f32_e32 v32, 0x3fb8aa3b, v36
	v_exp_f32_e32 v32, v32
	s_nop 0
	v_sub_f32_e32 v32, 1.0, v32
	s_or_b64 exec, exec, s[2:3]
	global_load_ushort v38, v[56:57], off offset:32
	v_add_f32_e32 v39, v39, v74
	v_add_f32_e32 v34, v34, v67
	v_mul_f32_e32 v39, 0xbfb8aa3b, v39
	v_mul_f32_e32 v34, 0xbfb8aa3b, v34
	v_exp_f32_e32 v39, v39
	v_exp_f32_e32 v34, v34
	v_max_f32_e32 v32, v32, v32
	v_max_f32_e32 v32, 0, v32
	v_add_f32_e32 v39, 1.0, v39
	v_rcp_f32_e32 v39, v39
	v_sqrt_f32_e32 v40, v32
	v_add_f32_e32 v32, 1.0, v34
	v_rcp_f32_e32 v41, v32
	v_mul_f32_e32 v32, v39, v72
	v_lshl_add_u64 v[36:37], v[54:55], 0, v[52:53]
	v_add_f32_e32 v34, v32, v32
	v_lshl_add_u64 v[36:37], v[36:37], 2, s[42:43]
	v_cmp_ngt_f32_e32 vcc, s9, v34
	s_waitcnt vmcnt(0)
	v_lshlrev_b32_e32 v38, 16, v38
	v_mul_f32_e32 v38, v41, v38
	v_mul_f32_e32 v38, v40, v38
	v_cvt_pk_bf16_f32 v33, v33, v38
	global_store_dword v[36:37], v33, off
	s_and_saveexec_b64 s[2:3], vcc
	s_xor_b64 s[2:3], exec, s[2:3]
	v_fmamk_f32 v33, v34, 0x3ab60b61, v169
	v_fmaak_f32 v33, v34, v33, 0x3d2aaaab
	v_fmaak_f32 v33, v34, v33, 0x3e2aaaab
	v_fma_f32 v33, v34, v33, 0.5
	v_fma_f32 v33, v34, v33, 1.0
	v_mul_f32_e64 v33, v33, -v34
	s_andn2_saveexec_b64 s[2:3], s[2:3]
	v_mul_f32_e32 v33, 0x3fb8aa3b, v34
	v_exp_f32_e32 v33, v33
	s_nop 0
	v_sub_f32_e32 v33, 1.0, v33
	s_or_b64 exec, exec, s[2:3]
	global_load_ushort v36, v[46:47], off offset:32
	v_add_f32_e32 v28, v28, v83
	v_add_f32_e32 v37, v35, v67
	v_mul_f32_e32 v28, 0xbfb8aa3b, v28
	v_mul_f32_e32 v37, 0xbfb8aa3b, v37
	v_exp_f32_e32 v28, v28
	v_exp_f32_e32 v37, v37
	v_max_f32_e32 v33, v33, v33
	v_max_f32_e32 v33, 0, v33
	v_add_f32_e32 v28, 1.0, v28
	v_rcp_f32_e32 v28, v28
	v_sqrt_f32_e32 v38, v33
	v_add_f32_e32 v33, 1.0, v37
	v_rcp_f32_e32 v37, v33
	v_mul_f32_e32 v28, v28, v84
	v_lshl_add_u64 v[34:35], v[42:43], 0, v[52:53]
	v_add_f32_e32 v33, v28, v28
	v_lshl_add_u64 v[34:35], v[34:35], 2, s[42:43]
	v_cmp_ngt_f32_e32 vcc, s9, v33
	s_waitcnt vmcnt(0)
	v_lshlrev_b32_e32 v36, 16, v36
	v_mul_f32_e32 v36, v37, v36
	v_mul_f32_e32 v36, v38, v36
	v_cvt_pk_bf16_f32 v32, v32, v36
	global_store_dword v[34:35], v32, off
	s_and_saveexec_b64 s[2:3], vcc
	s_xor_b64 s[2:3], exec, s[2:3]
	v_fmamk_f32 v32, v33, 0x3ab60b61, v169
	v_fmaak_f32 v32, v33, v32, 0x3d2aaaab
	v_fmaak_f32 v32, v33, v32, 0x3e2aaaab
	v_fma_f32 v32, v33, v32, 0.5
	v_fma_f32 v32, v33, v32, 1.0
	v_mul_f32_e64 v36, v32, -v33
	s_andn2_saveexec_b64 s[2:3], s[2:3]
	v_mul_f32_e32 v32, 0x3fb8aa3b, v33
	v_exp_f32_e32 v32, v32
	s_nop 0
	v_sub_f32_e32 v36, 1.0, v32
	s_or_b64 exec, exec, s[2:3]
	v_or_b32_e32 v32, 32, v66
	v_ashrrev_i32_e32 v33, 31, v32
	v_lshlrev_b64 v[32:33], 10, v[32:33]
	v_lshl_add_u64 v[38:39], v[32:33], 0, v[64:65]
	v_lshl_add_u64 v[34:35], v[38:39], 1, s[40:41]
	global_load_ushort v37, v[34:35], off
	v_add_f32_e32 v24, v24, v82
	v_mul_f32_e32 v24, 0xbfb8aa3b, v24
	v_exp_f32_e32 v24, v24
	v_max_f32_e32 v36, v36, v36
	v_max_f32_e32 v36, 0, v36
	v_sqrt_f32_e32 v36, v36
	v_add_f32_e32 v24, 1.0, v24
	v_rcp_f32_e32 v24, v24
	s_waitcnt vmcnt(0)
;   __host__ __device__ __forceinline__ bf16_t* XC() const { return (bf16_t*)(wsl() + OFF_FFN); }
; __device__ __forceinline__ float bf2f(bf16_t h) { return __uint_as_float(((uint32_t)h) << 16); }
; __device__ __forceinline__ uint32_t pack2(float a, float b) { uint32_t r; asm("v_cvt_pk_bf16_f32 %0, %1, %2" : "=v"(r) : "v"(a), "v"(b)); return r; }
; __device__ __forceinline__ float sigmoidf_(float x) { return __builtin_amdgcn_rcpf(1.0f + __expf(-x)); }
; template <int EPI>
; __device__ __forceinline__ void gemm_tile(const Params& p, const EpiArgs& ea, const bf16_t* __restrict__ A, int lda,
;                                           const bf16_t* __restrict__ Bt, int K, int m0, int n0, char* smem) {
;     ...
;         for (int j = 0; j < 4; ++j) {
;           float r = sigmoidf_(acc[mi][nh * 2][j] + ba);
;           float ig = sigmoidf_(acc[mi][nh * 2 + 1][j] + bx);
;           float la = r * sp8;
;           float x2 = 2.0f * la;
;           float poly = -x2 * (1.0f + x2 * (0.5f + x2 * (0.16666667f + x2 * (0.041666668f + x2 * (0.008333334f + x2 * 0.0013888889f)))));
;           float em = (x2 < -0.3f) ? (1.0f - __expf(x2)) : poly;
;           float u = bf2f(p.XC()[(size_t)(r0 + j) * D + ch]);
;           float inp = __builtin_amdgcn_sqrtf(fmaxf(em, 0.0f)) * (ig * u);
;           ea.outu[(size_t)(r0 + j) * D + ch] = pack2(la, inp);
	v_lshlrev_b32_e32 v37, 16, v37
	v_mul_f32_e32 v24, v24, v37
	v_mul_f32_e32 v24, v36, v24
	v_cvt_pk_bf16_f32 v24, v28, v24
	v_lshl_add_u64 v[36:37], v[38:39], 2, s[42:43]
	global_store_dword v[36:37], v24, off
	v_add_f32_e32 v24, v29, v83
	v_mul_f32_e32 v24, 0xbfb8aa3b, v24
	v_exp_f32_e32 v24, v24
	s_nop 0
	v_add_f32_e32 v24, 1.0, v24
	v_rcp_f32_e32 v24, v24
	s_nop 0
	v_mul_f32_e32 v36, v24, v84
	v_add_f32_e32 v24, v36, v36
	v_cmp_ngt_f32_e32 vcc, s9, v24
	s_and_saveexec_b64 s[2:3], vcc
	s_xor_b64 s[2:3], exec, s[2:3]
	v_fmamk_f32 v28, v24, 0x3ab60b61, v169
	v_fmaak_f32 v28, v24, v28, 0x3d2aaaab
	v_fmaak_f32 v28, v24, v28, 0x3e2aaaab
	v_fma_f32 v28, v24, v28, 0.5
	v_fma_f32 v28, v24, v28, 1.0
	v_mul_f32_e64 v37, v28, -v24
	s_andn2_saveexec_b64 s[2:3], s[2:3]
	v_mul_f32_e32 v24, 0x3fb8aa3b, v24
	v_exp_f32_e32 v24, v24
	s_nop 0
	v_sub_f32_e32 v37, 1.0, v24
	s_or_b64 exec, exec, s[2:3]
	v_add_f32_e32 v24, v25, v82
	v_mul_f32_e32 v24, 0xbfb8aa3b, v24
	v_exp_f32_e32 v24, v24
	v_add_f32_e32 v30, v30, v83
	v_mul_f32_e32 v30, 0xbfb8aa3b, v30
	v_exp_f32_e32 v30, v30
	v_add_f32_e32 v24, 1.0, v24
	v_rcp_f32_e32 v40, v24
	v_or_b32_e32 v24, 33, v66
	v_ashrrev_i32_e32 v25, 31, v24
	v_lshlrev_b64 v[24:25], 10, v[24:25]
	v_lshl_add_u64 v[38:39], v[24:25], 0, v[64:65]
	v_lshl_add_u64 v[28:29], v[38:39], 1, s[40:41]
	global_load_ushort v41, v[28:29], off
	v_max_f32_e32 v37, v37, v37
	v_max_f32_e32 v37, 0, v37
	v_sqrt_f32_e32 v37, v37
	v_add_f32_e32 v30, 1.0, v30
	v_rcp_f32_e32 v30, v30
	s_waitcnt vmcnt(0)
	v_lshlrev_b32_e32 v41, 16, v41
	v_mul_f32_e32 v40, v40, v41
	v_mul_f32_e32 v37, v37, v40
	v_cvt_pk_bf16_f32 v40, v36, v37
	v_lshl_add_u64 v[36:37], v[38:39], 2, s[42:43]
	v_mul_f32_e32 v30, v30, v84
	global_store_dword v[36:37], v40, off
	v_add_f32_e32 v36, v30, v30
	v_cmp_ngt_f32_e32 vcc, s9, v36
	s_and_saveexec_b64 s[2:3], vcc
	s_xor_b64 s[2:3], exec, s[2:3]
	v_fmamk_f32 v37, v36, 0x3ab60b61, v169
	v_fmaak_f32 v37, v36, v37, 0x3d2aaaab
	v_fmaak_f32 v37, v36, v37, 0x3e2aaaab
	v_fma_f32 v37, v36, v37, 0.5
	v_fma_f32 v37, v36, v37, 1.0
	v_mul_f32_e64 v40, v37, -v36
	s_andn2_saveexec_b64 s[2:3], s[2:3]
	v_mul_f32_e32 v36, 0x3fb8aa3b, v36
	v_exp_f32_e32 v36, v36
	s_nop 0
	v_sub_f32_e32 v40, 1.0, v36
	s_or_b64 exec, exec, s[2:3]
	v_or_b32_e32 v36, 34, v66
	v_ashrrev_i32_e32 v37, 31, v36
	v_lshlrev_b64 v[36:37], 10, v[36:37]
	v_lshl_add_u64 v[42:43], v[36:37], 0, v[64:65]
	v_lshl_add_u64 v[38:39], v[42:43], 1, s[40:41]
	global_load_ushort v41, v[38:39], off
	v_add_f32_e32 v31, v31, v83
	v_mul_f32_e32 v31, 0xbfb8aa3b, v31
	v_add_f32_e32 v26, v26, v82
	v_exp_f32_e32 v31, v31
	v_mul_f32_e32 v26, 0xbfb8aa3b, v26
	v_exp_f32_e32 v26, v26
	v_max_f32_e32 v40, v40, v40
	v_add_f32_e32 v31, 1.0, v31
	v_rcp_f32_e32 v31, v31
	v_add_f32_e32 v26, 1.0, v26
	v_max_f32_e32 v40, 0, v40
	v_rcp_f32_e32 v45, v26
	v_sqrt_f32_e32 v44, v40
	v_mul_f32_e32 v40, v31, v84
	v_add_f32_e32 v26, v40, v40
	v_lshl_add_u64 v[42:43], v[42:43], 2, s[42:43]
	v_cmp_ngt_f32_e32 vcc, s9, v26
	s_waitcnt vmcnt(0)
	v_lshlrev_b32_e32 v31, 16, v41
	v_mul_f32_e32 v31, v45, v31
	v_mul_f32_e32 v31, v44, v31
	v_cvt_pk_bf16_f32 v30, v30, v31
	global_store_dword v[42:43], v30, off
	s_and_saveexec_b64 s[2:3], vcc
	s_xor_b64 s[2:3], exec, s[2:3]
	v_fmamk_f32 v30, v26, 0x3ab60b61, v169
	v_fmaak_f32 v30, v26, v30, 0x3d2aaaab
	v_fmaak_f32 v30, v26, v30, 0x3e2aaaab
	v_fma_f32 v30, v26, v30, 0.5
	v_fma_f32 v30, v26, v30, 1.0
	v_mul_f32_e64 v41, v30, -v26
	s_andn2_saveexec_b64 s[2:3], s[2:3]
	v_mul_f32_e32 v26, 0x3fb8aa3b, v26
	v_exp_f32_e32 v26, v26
	s_nop 0
	v_sub_f32_e32 v41, 1.0, v26
	s_or_b64 exec, exec, s[2:3]
	v_add_f32_e32 v26, v27, v82
	v_mul_f32_e32 v26, 0xbfb8aa3b, v26
	v_exp_f32_e32 v26, v26
	v_add_f32_e32 v20, v20, v74
	v_mul_f32_e32 v20, 0xbfb8aa3b, v20
	v_exp_f32_e32 v20, v20
	v_add_f32_e32 v26, 1.0, v26
	v_rcp_f32_e32 v44, v26
	v_or_b32_e32 v26, 35, v66
	v_ashrrev_i32_e32 v27, 31, v26
	v_lshlrev_b64 v[26:27], 10, v[26:27]
	v_lshl_add_u64 v[42:43], v[26:27], 0, v[64:65]
	v_lshl_add_u64 v[30:31], v[42:43], 1, s[40:41]
	global_load_ushort v45, v[30:31], off
	v_max_f32_e32 v41, v41, v41
	v_max_f32_e32 v41, 0, v41
	v_sqrt_f32_e32 v41, v41
	v_add_f32_e32 v20, 1.0, v20
	v_rcp_f32_e32 v20, v20
	s_waitcnt vmcnt(0)
	v_lshlrev_b32_e32 v45, 16, v45
	v_mul_f32_e32 v44, v44, v45
	v_mul_f32_e32 v41, v41, v44
	v_cvt_pk_bf16_f32 v44, v40, v41
	v_lshl_add_u64 v[40:41], v[42:43], 2, s[42:43]
	v_mul_f32_e32 v20, v20, v72
	global_store_dword v[40:41], v44, off
	v_add_f32_e32 v40, v20, v20
	v_cmp_ngt_f32_e32 vcc, s9, v40
	s_and_saveexec_b64 s[2:3], vcc
	s_xor_b64 s[2:3], exec, s[2:3]
	v_fmamk_f32 v41, v40, 0x3ab60b61, v169
	v_fmaak_f32 v41, v40, v41, 0x3d2aaaab
	v_fmaak_f32 v41, v40, v41, 0x3e2aaaab
	v_fma_f32 v41, v40, v41, 0.5
	v_fma_f32 v41, v40, v41, 1.0
	v_mul_f32_e64 v41, v41, -v40
	s_andn2_saveexec_b64 s[2:3], s[2:3]
	v_mul_f32_e32 v40, 0x3fb8aa3b, v40
	v_exp_f32_e32 v40, v40
	s_nop 0
	v_sub_f32_e32 v41, 1.0, v40
	s_or_b64 exec, exec, s[2:3]
	global_load_ushort v34, v[34:35], off offset:32
	v_add_f32_e32 v21, v21, v74
	v_add_f32_e32 v16, v16, v67
	v_mul_f32_e32 v21, 0xbfb8aa3b, v21
	v_mul_f32_e32 v16, 0xbfb8aa3b, v16
	v_exp_f32_e32 v21, v21
	v_exp_f32_e32 v16, v16
	v_max_f32_e32 v35, v41, v41
	v_max_f32_e32 v35, 0, v35
	v_add_f32_e32 v21, 1.0, v21
	v_rcp_f32_e32 v21, v21
	v_add_f32_e32 v16, 1.0, v16
	v_rcp_f32_e32 v40, v16
	v_sqrt_f32_e32 v35, v35
	v_mul_f32_e32 v16, v21, v72
	v_lshl_add_u64 v[32:33], v[32:33], 0, v[52:53]
	v_add_f32_e32 v21, v16, v16
	v_lshl_add_u64 v[32:33], v[32:33], 2, s[42:43]
	v_cmp_ngt_f32_e32 vcc, s9, v21
	s_waitcnt vmcnt(0)
;   __host__ __device__ __forceinline__ bf16_t* XC() const { return (bf16_t*)(wsl() + OFF_FFN); }
; __device__ __forceinline__ float bf2f(bf16_t h) { return __uint_as_float(((uint32_t)h) << 16); }
; __device__ __forceinline__ uint32_t pack2(float a, float b) { uint32_t r; asm("v_cvt_pk_bf16_f32 %0, %1, %2" : "=v"(r) : "v"(a), "v"(b)); return r; }
; __device__ __forceinline__ float sigmoidf_(float x) { return __builtin_amdgcn_rcpf(1.0f + __expf(-x)); }
; template <int EPI>
; __device__ __forceinline__ void gemm_tile(const Params& p, const EpiArgs& ea, const bf16_t* __restrict__ A, int lda,
;                                           const bf16_t* __restrict__ Bt, int K, int m0, int n0, char* smem) {
;     ...
;         for (int j = 0; j < 4; ++j) {
;           float r = sigmoidf_(acc[mi][nh * 2][j] + ba);
;           float ig = sigmoidf_(acc[mi][nh * 2 + 1][j] + bx);
;           float la = r * sp8;
;           float x2 = 2.0f * la;
;           float poly = -x2 * (1.0f + x2 * (0.5f + x2 * (0.16666667f + x2 * (0.041666668f + x2 * (0.008333334f + x2 * 0.0013888889f)))));
;           float em = (x2 < -0.3f) ? (1.0f - __expf(x2)) : poly;
;           float u = bf2f(p.XC()[(size_t)(r0 + j) * D + ch]);
;           float inp = __builtin_amdgcn_sqrtf(fmaxf(em, 0.0f)) * (ig * u);
;           ea.outu[(size_t)(r0 + j) * D + ch] = pack2(la, inp);
	v_lshlrev_b32_e32 v34, 16, v34
	v_mul_f32_e32 v34, v40, v34
	v_mul_f32_e32 v34, v35, v34
	v_cvt_pk_bf16_f32 v20, v20, v34
	global_store_dword v[32:33], v20, off
	s_and_saveexec_b64 s[2:3], vcc
	s_xor_b64 s[2:3], exec, s[2:3]
	v_fmamk_f32 v20, v21, 0x3ab60b61, v169
	v_fmaak_f32 v20, v21, v20, 0x3d2aaaab
	v_fmaak_f32 v20, v21, v20, 0x3e2aaaab
	v_fma_f32 v20, v21, v20, 0.5
	v_fma_f32 v20, v21, v20, 1.0
	v_mul_f32_e64 v20, v20, -v21
	s_andn2_saveexec_b64 s[2:3], s[2:3]
	v_mul_f32_e32 v20, 0x3fb8aa3b, v21
	v_exp_f32_e32 v20, v20
	s_nop 0
	v_sub_f32_e32 v20, 1.0, v20
	s_or_b64 exec, exec, s[2:3]
	global_load_ushort v21, v[28:29], off offset:32
	v_add_f32_e32 v22, v22, v74
	v_add_f32_e32 v17, v17, v67
	v_mul_f32_e32 v22, 0xbfb8aa3b, v22
	v_mul_f32_e32 v17, 0xbfb8aa3b, v17
	v_exp_f32_e32 v22, v22
	v_exp_f32_e32 v17, v17
	v_max_f32_e32 v20, v20, v20
	v_max_f32_e32 v20, 0, v20
	v_add_f32_e32 v22, 1.0, v22
	v_rcp_f32_e32 v22, v22
	v_add_f32_e32 v17, 1.0, v17
	v_rcp_f32_e32 v29, v17
	v_sqrt_f32_e32 v28, v20
	v_mul_f32_e32 v17, v22, v72
	v_lshl_add_u64 v[24:25], v[24:25], 0, v[52:53]
	v_add_f32_e32 v20, v17, v17
	v_lshl_add_u64 v[24:25], v[24:25], 2, s[42:43]
	v_cmp_ngt_f32_e32 vcc, s9, v20
	s_waitcnt vmcnt(0)
	v_lshlrev_b32_e32 v21, 16, v21
	v_mul_f32_e32 v21, v29, v21
	v_mul_f32_e32 v21, v28, v21
	v_cvt_pk_bf16_f32 v16, v16, v21
	global_store_dword v[24:25], v16, off
	s_and_saveexec_b64 s[2:3], vcc
	s_xor_b64 s[2:3], exec, s[2:3]
	v_fmamk_f32 v16, v20, 0x3ab60b61, v169
	v_fmaak_f32 v16, v20, v16, 0x3d2aaaab
	v_fmaak_f32 v16, v20, v16, 0x3e2aaaab
	v_fma_f32 v16, v20, v16, 0.5
	v_fma_f32 v16, v20, v16, 1.0
	v_mul_f32_e64 v16, v16, -v20
	s_andn2_saveexec_b64 s[2:3], s[2:3]
	v_mul_f32_e32 v16, 0x3fb8aa3b, v20
	v_exp_f32_e32 v16, v16
	s_nop 0
	v_sub_f32_e32 v16, 1.0, v16
	s_or_b64 exec, exec, s[2:3]
	global_load_ushort v22, v[38:39], off offset:32
	v_add_f32_e32 v23, v23, v74
	v_add_f32_e32 v18, v18, v67
	v_mul_f32_e32 v23, 0xbfb8aa3b, v23
	v_mul_f32_e32 v18, 0xbfb8aa3b, v18
	v_exp_f32_e32 v23, v23
	v_exp_f32_e32 v18, v18
	v_max_f32_e32 v16, v16, v16
	v_max_f32_e32 v16, 0, v16
	v_add_f32_e32 v23, 1.0, v23
	v_rcp_f32_e32 v23, v23
	v_sqrt_f32_e32 v24, v16
	v_add_f32_e32 v16, 1.0, v18
	v_rcp_f32_e32 v25, v16
	v_mul_f32_e32 v16, v23, v72
	v_lshl_add_u64 v[20:21], v[36:37], 0, v[52:53]
	v_add_f32_e32 v18, v16, v16
	v_lshl_add_u64 v[20:21], v[20:21], 2, s[42:43]
	v_cmp_ngt_f32_e32 vcc, s9, v18
	s_waitcnt vmcnt(0)
	v_lshlrev_b32_e32 v22, 16, v22
	v_mul_f32_e32 v22, v25, v22
	v_mul_f32_e32 v22, v24, v22
	v_cvt_pk_bf16_f32 v17, v17, v22
	global_store_dword v[20:21], v17, off
	s_and_saveexec_b64 s[2:3], vcc
	s_xor_b64 s[2:3], exec, s[2:3]
	v_fmamk_f32 v17, v18, 0x3ab60b61, v169
	v_fmaak_f32 v17, v18, v17, 0x3d2aaaab
	v_fmaak_f32 v17, v18, v17, 0x3e2aaaab
	v_fma_f32 v17, v18, v17, 0.5
	v_fma_f32 v17, v18, v17, 1.0
	v_mul_f32_e64 v17, v17, -v18
	s_andn2_saveexec_b64 s[2:3], s[2:3]
	v_mul_f32_e32 v17, 0x3fb8aa3b, v18
	v_exp_f32_e32 v17, v17
	s_nop 0
	v_sub_f32_e32 v17, 1.0, v17
	s_or_b64 exec, exec, s[2:3]
	global_load_ushort v20, v[30:31], off offset:32
	v_add_f32_e32 v12, v12, v83
	v_add_f32_e32 v21, v19, v67
	v_mul_f32_e32 v12, 0xbfb8aa3b, v12
	v_mul_f32_e32 v21, 0xbfb8aa3b, v21
	v_exp_f32_e32 v12, v12
	v_exp_f32_e32 v21, v21
	v_max_f32_e32 v17, v17, v17
	v_max_f32_e32 v17, 0, v17
	v_add_f32_e32 v12, 1.0, v12
	v_rcp_f32_e32 v12, v12
	v_sqrt_f32_e32 v22, v17
	v_add_f32_e32 v17, 1.0, v21
	v_rcp_f32_e32 v21, v17
	v_mul_f32_e32 v12, v12, v84
	v_lshl_add_u64 v[18:19], v[26:27], 0, v[52:53]
	v_add_f32_e32 v17, v12, v12
	v_lshl_add_u64 v[18:19], v[18:19], 2, s[42:43]
	v_cmp_ngt_f32_e32 vcc, s9, v17
	s_waitcnt vmcnt(0)
	v_lshlrev_b32_e32 v20, 16, v20
	v_mul_f32_e32 v20, v21, v20
	v_mul_f32_e32 v20, v22, v20
	v_cvt_pk_bf16_f32 v16, v16, v20
	global_store_dword v[18:19], v16, off
	s_and_saveexec_b64 s[2:3], vcc
	s_xor_b64 s[2:3], exec, s[2:3]
	v_fmamk_f32 v16, v17, 0x3ab60b61, v169
	v_fmaak_f32 v16, v17, v16, 0x3d2aaaab
	v_fmaak_f32 v16, v17, v16, 0x3e2aaaab
	v_fma_f32 v16, v17, v16, 0.5
	v_fma_f32 v16, v17, v16, 1.0
	v_mul_f32_e64 v20, v16, -v17
	s_andn2_saveexec_b64 s[2:3], s[2:3]
	v_mul_f32_e32 v16, 0x3fb8aa3b, v17
	v_exp_f32_e32 v16, v16
	s_nop 0
	v_sub_f32_e32 v20, 1.0, v16
	s_or_b64 exec, exec, s[2:3]
	v_or_b32_e32 v16, 48, v66
	v_ashrrev_i32_e32 v17, 31, v16
	v_lshlrev_b64 v[16:17], 10, v[16:17]
	v_lshl_add_u64 v[22:23], v[16:17], 0, v[64:65]
	v_lshl_add_u64 v[18:19], v[22:23], 1, s[40:41]
	global_load_ushort v21, v[18:19], off
	v_add_f32_e32 v8, v8, v82
	v_mul_f32_e32 v8, 0xbfb8aa3b, v8
	v_exp_f32_e32 v8, v8
	v_max_f32_e32 v20, v20, v20
	v_max_f32_e32 v20, 0, v20
	v_sqrt_f32_e32 v20, v20
	v_add_f32_e32 v8, 1.0, v8
	v_rcp_f32_e32 v8, v8
	s_waitcnt vmcnt(0)
	v_lshlrev_b32_e32 v21, 16, v21
	v_mul_f32_e32 v8, v8, v21
	v_mul_f32_e32 v8, v20, v8
	v_cvt_pk_bf16_f32 v8, v12, v8
	v_lshl_add_u64 v[20:21], v[22:23], 2, s[42:43]
	global_store_dword v[20:21], v8, off
	v_add_f32_e32 v8, v13, v83
	v_mul_f32_e32 v8, 0xbfb8aa3b, v8
	v_exp_f32_e32 v8, v8
	s_nop 0
	v_add_f32_e32 v8, 1.0, v8
	v_rcp_f32_e32 v8, v8
	s_nop 0
	v_mul_f32_e32 v20, v8, v84
	v_add_f32_e32 v8, v20, v20
	v_cmp_ngt_f32_e32 vcc, s9, v8
	s_and_saveexec_b64 s[2:3], vcc
	s_xor_b64 s[2:3], exec, s[2:3]
	v_fmamk_f32 v12, v8, 0x3ab60b61, v169
	v_fmaak_f32 v12, v8, v12, 0x3d2aaaab
	v_fmaak_f32 v12, v8, v12, 0x3e2aaaab
	v_fma_f32 v12, v8, v12, 0.5
	v_fma_f32 v12, v8, v12, 1.0
	v_mul_f32_e64 v21, v12, -v8
	s_andn2_saveexec_b64 s[2:3], s[2:3]
	v_mul_f32_e32 v8, 0x3fb8aa3b, v8
	v_exp_f32_e32 v8, v8
	s_nop 0
	v_sub_f32_e32 v21, 1.0, v8
	s_or_b64 exec, exec, s[2:3]
	v_add_f32_e32 v8, v9, v82
	v_mul_f32_e32 v8, 0xbfb8aa3b, v8
	v_exp_f32_e32 v8, v8
	v_add_f32_e32 v14, v14, v83
	v_mul_f32_e32 v14, 0xbfb8aa3b, v14
	v_exp_f32_e32 v14, v14
	v_add_f32_e32 v8, 1.0, v8
	v_rcp_f32_e32 v24, v8
	v_or_b32_e32 v8, 49, v66
	v_ashrrev_i32_e32 v9, 31, v8
	v_lshlrev_b64 v[8:9], 10, v[8:9]
	v_lshl_add_u64 v[22:23], v[8:9], 0, v[64:65]
	v_lshl_add_u64 v[12:13], v[22:23], 1, s[40:41]
	global_load_ushort v25, v[12:13], off
	v_max_f32_e32 v21, v21, v21
	v_max_f32_e32 v21, 0, v21
	v_sqrt_f32_e32 v21, v21
	v_add_f32_e32 v14, 1.0, v14
	v_rcp_f32_e32 v14, v14
	s_waitcnt vmcnt(0)
;   __host__ __device__ __forceinline__ bf16_t* XC() const { return (bf16_t*)(wsl() + OFF_FFN); }
; __device__ __forceinline__ float bf2f(bf16_t h) { return __uint_as_float(((uint32_t)h) << 16); }
; __device__ __forceinline__ uint32_t pack2(float a, float b) { uint32_t r; asm("v_cvt_pk_bf16_f32 %0, %1, %2" : "=v"(r) : "v"(a), "v"(b)); return r; }
; __device__ __forceinline__ float sigmoidf_(float x) { return __builtin_amdgcn_rcpf(1.0f + __expf(-x)); }
; template <int EPI>
; __device__ __forceinline__ void gemm_tile(const Params& p, const EpiArgs& ea, const bf16_t* __restrict__ A, int lda,
;                                           const bf16_t* __restrict__ Bt, int K, int m0, int n0, char* smem) {
;     ...
;         for (int j = 0; j < 4; ++j) {
;           float r = sigmoidf_(acc[mi][nh * 2][j] + ba);
;           float ig = sigmoidf_(acc[mi][nh * 2 + 1][j] + bx);
;           float la = r * sp8;
;           float x2 = 2.0f * la;
;           float poly = -x2 * (1.0f + x2 * (0.5f + x2 * (0.16666667f + x2 * (0.041666668f + x2 * (0.008333334f + x2 * 0.0013888889f)))));
;           float em = (x2 < -0.3f) ? (1.0f - __expf(x2)) : poly;
;           float u = bf2f(p.XC()[(size_t)(r0 + j) * D + ch]);
;           float inp = __builtin_amdgcn_sqrtf(fmaxf(em, 0.0f)) * (ig * u);
;           ea.outu[(size_t)(r0 + j) * D + ch] = pack2(la, inp);
	v_lshlrev_b32_e32 v25, 16, v25
	v_mul_f32_e32 v24, v24, v25
	v_mul_f32_e32 v21, v21, v24
	v_cvt_pk_bf16_f32 v24, v20, v21
	v_lshl_add_u64 v[20:21], v[22:23], 2, s[42:43]
	v_mul_f32_e32 v14, v14, v84
	global_store_dword v[20:21], v24, off
	v_add_f32_e32 v20, v14, v14
	v_cmp_ngt_f32_e32 vcc, s9, v20
	s_and_saveexec_b64 s[2:3], vcc
	s_xor_b64 s[2:3], exec, s[2:3]
	v_fmamk_f32 v21, v20, 0x3ab60b61, v169
	v_fmaak_f32 v21, v20, v21, 0x3d2aaaab
	v_fmaak_f32 v21, v20, v21, 0x3e2aaaab
	v_fma_f32 v21, v20, v21, 0.5
	v_fma_f32 v21, v20, v21, 1.0
	v_mul_f32_e64 v24, v21, -v20
	s_andn2_saveexec_b64 s[2:3], s[2:3]
	v_mul_f32_e32 v20, 0x3fb8aa3b, v20
	v_exp_f32_e32 v20, v20
	s_nop 0
	v_sub_f32_e32 v24, 1.0, v20
	s_or_b64 exec, exec, s[2:3]
	v_or_b32_e32 v20, 50, v66
	v_ashrrev_i32_e32 v21, 31, v20
	v_lshlrev_b64 v[20:21], 10, v[20:21]
	v_lshl_add_u64 v[26:27], v[20:21], 0, v[64:65]
	v_lshl_add_u64 v[22:23], v[26:27], 1, s[40:41]
	global_load_ushort v25, v[22:23], off
	v_add_f32_e32 v15, v15, v83
	v_mul_f32_e32 v15, 0xbfb8aa3b, v15
	v_add_f32_e32 v10, v10, v82
	v_exp_f32_e32 v15, v15
	v_mul_f32_e32 v10, 0xbfb8aa3b, v10
	v_exp_f32_e32 v10, v10
	v_max_f32_e32 v24, v24, v24
	v_add_f32_e32 v15, 1.0, v15
	v_rcp_f32_e32 v15, v15
	v_add_f32_e32 v10, 1.0, v10
	v_max_f32_e32 v24, 0, v24
	v_rcp_f32_e32 v29, v10
	v_sqrt_f32_e32 v28, v24
	v_mul_f32_e32 v24, v15, v84
	v_add_f32_e32 v10, v24, v24
	v_lshl_add_u64 v[26:27], v[26:27], 2, s[42:43]
	v_cmp_ngt_f32_e32 vcc, s9, v10
	s_waitcnt vmcnt(0)
	v_lshlrev_b32_e32 v15, 16, v25
	v_mul_f32_e32 v15, v29, v15
	v_mul_f32_e32 v15, v28, v15
	v_cvt_pk_bf16_f32 v14, v14, v15
	global_store_dword v[26:27], v14, off
	s_and_saveexec_b64 s[2:3], vcc
	s_xor_b64 s[2:3], exec, s[2:3]
	v_fmamk_f32 v14, v10, 0x3ab60b61, v169
	v_fmaak_f32 v14, v10, v14, 0x3d2aaaab
	v_fmaak_f32 v14, v10, v14, 0x3e2aaaab
	v_fma_f32 v14, v10, v14, 0.5
	v_fma_f32 v14, v10, v14, 1.0
	v_mul_f32_e64 v25, v14, -v10
	s_andn2_saveexec_b64 s[2:3], s[2:3]
	v_mul_f32_e32 v10, 0x3fb8aa3b, v10
	v_exp_f32_e32 v10, v10
	s_nop 0
	v_sub_f32_e32 v25, 1.0, v10
	s_or_b64 exec, exec, s[2:3]
	v_add_f32_e32 v10, v11, v82
	v_mul_f32_e32 v10, 0xbfb8aa3b, v10
	v_exp_f32_e32 v10, v10
	v_add_f32_e32 v4, v4, v74
	v_mul_f32_e32 v4, 0xbfb8aa3b, v4
	v_exp_f32_e32 v4, v4
	v_add_f32_e32 v10, 1.0, v10
	v_rcp_f32_e32 v28, v10
	v_or_b32_e32 v10, 51, v66
	v_ashrrev_i32_e32 v11, 31, v10
	v_lshlrev_b64 v[10:11], 10, v[10:11]
	v_lshl_add_u64 v[26:27], v[10:11], 0, v[64:65]
	v_lshl_add_u64 v[14:15], v[26:27], 1, s[40:41]
	global_load_ushort v29, v[14:15], off
	v_max_f32_e32 v25, v25, v25
	v_max_f32_e32 v25, 0, v25
	v_sqrt_f32_e32 v25, v25
	v_add_f32_e32 v4, 1.0, v4
	v_rcp_f32_e32 v4, v4
	s_waitcnt vmcnt(0)
	v_lshlrev_b32_e32 v29, 16, v29
	v_mul_f32_e32 v28, v28, v29
	v_mul_f32_e32 v25, v25, v28
	v_cvt_pk_bf16_f32 v28, v24, v25
	v_lshl_add_u64 v[24:25], v[26:27], 2, s[42:43]
	v_mul_f32_e32 v4, v4, v72
	global_store_dword v[24:25], v28, off
	v_add_f32_e32 v24, v4, v4
	v_cmp_ngt_f32_e32 vcc, s9, v24
	s_and_saveexec_b64 s[2:3], vcc
	s_xor_b64 s[2:3], exec, s[2:3]
	v_fmamk_f32 v25, v24, 0x3ab60b61, v169
	v_fmaak_f32 v25, v24, v25, 0x3d2aaaab
	v_fmaak_f32 v25, v24, v25, 0x3e2aaaab
	v_fma_f32 v25, v24, v25, 0.5
	v_fma_f32 v25, v24, v25, 1.0
	v_mul_f32_e64 v25, v25, -v24
	s_andn2_saveexec_b64 s[2:3], s[2:3]
	v_mul_f32_e32 v24, 0x3fb8aa3b, v24
	v_exp_f32_e32 v24, v24
	s_nop 0
	v_sub_f32_e32 v25, 1.0, v24
	s_or_b64 exec, exec, s[2:3]
	global_load_ushort v18, v[18:19], off offset:32
	v_add_f32_e32 v5, v5, v74
	v_add_f32_e32 v0, v0, v67
	v_mul_f32_e32 v5, 0xbfb8aa3b, v5
	v_mul_f32_e32 v0, 0xbfb8aa3b, v0
	v_exp_f32_e32 v5, v5
	v_exp_f32_e32 v0, v0
	v_max_f32_e32 v19, v25, v25
	v_max_f32_e32 v19, 0, v19
	v_add_f32_e32 v5, 1.0, v5
	v_rcp_f32_e32 v5, v5
	v_add_f32_e32 v0, 1.0, v0
	v_rcp_f32_e32 v24, v0
	v_sqrt_f32_e32 v19, v19
	v_mul_f32_e32 v0, v5, v72
	v_lshl_add_u64 v[16:17], v[16:17], 0, v[52:53]
	v_add_f32_e32 v5, v0, v0
	v_lshl_add_u64 v[16:17], v[16:17], 2, s[42:43]
	v_cmp_ngt_f32_e32 vcc, s9, v5
	s_waitcnt vmcnt(0)
;   __host__ __device__ __forceinline__ bf16_t* XC() const { return (bf16_t*)(wsl() + OFF_FFN); }
; __device__ __forceinline__ float bf2f(bf16_t h) { return __uint_as_float(((uint32_t)h) << 16); }
; __device__ __forceinline__ uint32_t pack2(float a, float b) { uint32_t r; asm("v_cvt_pk_bf16_f32 %0, %1, %2" : "=v"(r) : "v"(a), "v"(b)); return r; }
; __device__ __forceinline__ float sigmoidf_(float x) { return __builtin_amdgcn_rcpf(1.0f + __expf(-x)); }
; template <int EPI>
; __device__ __forceinline__ void gemm_tile(const Params& p, const EpiArgs& ea, const bf16_t* __restrict__ A, int lda,
;                                           const bf16_t* __restrict__ Bt, int K, int m0, int n0, char* smem) {
;     ...
;         for (int j = 0; j < 4; ++j) {
;           float r = sigmoidf_(acc[mi][nh * 2][j] + ba);
;           float ig = sigmoidf_(acc[mi][nh * 2 + 1][j] + bx);
;           float la = r * sp8;
;           float x2 = 2.0f * la;
;           float poly = -x2 * (1.0f + x2 * (0.5f + x2 * (0.16666667f + x2 * (0.041666668f + x2 * (0.008333334f + x2 * 0.0013888889f)))));
;           float em = (x2 < -0.3f) ? (1.0f - __expf(x2)) : poly;
;           float u = bf2f(p.XC()[(size_t)(r0 + j) * D + ch]);
;           float inp = __builtin_amdgcn_sqrtf(fmaxf(em, 0.0f)) * (ig * u);
;           ea.outu[(size_t)(r0 + j) * D + ch] = pack2(la, inp);
	v_lshlrev_b32_e32 v18, 16, v18
	v_mul_f32_e32 v18, v24, v18
	v_mul_f32_e32 v18, v19, v18
	v_cvt_pk_bf16_f32 v4, v4, v18
	global_store_dword v[16:17], v4, off
	s_and_saveexec_b64 s[2:3], vcc
	s_xor_b64 s[2:3], exec, s[2:3]
	v_fmamk_f32 v4, v5, 0x3ab60b61, v169
	v_fmaak_f32 v4, v5, v4, 0x3d2aaaab
	v_fmaak_f32 v4, v5, v4, 0x3e2aaaab
	v_fma_f32 v4, v5, v4, 0.5
	v_fma_f32 v4, v5, v4, 1.0
	v_mul_f32_e64 v4, v4, -v5
	s_andn2_saveexec_b64 s[2:3], s[2:3]
	v_mul_f32_e32 v4, 0x3fb8aa3b, v5
	v_exp_f32_e32 v4, v4
	s_nop 0
	v_sub_f32_e32 v4, 1.0, v4
	s_or_b64 exec, exec, s[2:3]
	global_load_ushort v5, v[12:13], off offset:32
	v_add_f32_e32 v6, v6, v74
	v_add_f32_e32 v1, v1, v67
	v_mul_f32_e32 v6, 0xbfb8aa3b, v6
	v_mul_f32_e32 v1, 0xbfb8aa3b, v1
	v_exp_f32_e32 v6, v6
	v_exp_f32_e32 v1, v1
	v_max_f32_e32 v4, v4, v4
	v_max_f32_e32 v4, 0, v4
	v_add_f32_e32 v6, 1.0, v6
	v_rcp_f32_e32 v6, v6
	v_add_f32_e32 v1, 1.0, v1
	v_rcp_f32_e32 v13, v1
	v_sqrt_f32_e32 v12, v4
	v_mul_f32_e32 v1, v6, v72
	v_lshl_add_u64 v[8:9], v[8:9], 0, v[52:53]
	v_add_f32_e32 v4, v1, v1
	v_lshl_add_u64 v[8:9], v[8:9], 2, s[42:43]
	v_cmp_ngt_f32_e32 vcc, s9, v4
	s_waitcnt vmcnt(0)
	v_lshlrev_b32_e32 v5, 16, v5
	v_mul_f32_e32 v5, v13, v5
	v_mul_f32_e32 v5, v12, v5
	v_cvt_pk_bf16_f32 v0, v0, v5
	global_store_dword v[8:9], v0, off
	s_and_saveexec_b64 s[2:3], vcc
	s_xor_b64 s[2:3], exec, s[2:3]
	v_fmamk_f32 v0, v4, 0x3ab60b61, v169
	v_fmaak_f32 v0, v4, v0, 0x3d2aaaab
	v_fmaak_f32 v0, v4, v0, 0x3e2aaaab
	v_fma_f32 v0, v4, v0, 0.5
	v_fma_f32 v0, v4, v0, 1.0
	v_mul_f32_e64 v0, v0, -v4
	s_andn2_saveexec_b64 s[2:3], s[2:3]
	v_mul_f32_e32 v0, 0x3fb8aa3b, v4
	v_exp_f32_e32 v0, v0
	s_nop 0
	v_sub_f32_e32 v0, 1.0, v0
	s_or_b64 exec, exec, s[2:3]
	global_load_ushort v6, v[22:23], off offset:32
	v_add_f32_e32 v7, v7, v74
	v_add_f32_e32 v2, v2, v67
	v_mul_f32_e32 v7, 0xbfb8aa3b, v7
	v_mul_f32_e32 v2, 0xbfb8aa3b, v2
	v_exp_f32_e32 v7, v7
	v_exp_f32_e32 v2, v2
	v_max_f32_e32 v0, v0, v0
	v_max_f32_e32 v0, 0, v0
	v_add_f32_e32 v7, 1.0, v7
	v_rcp_f32_e32 v7, v7
	v_sqrt_f32_e32 v8, v0
	v_add_f32_e32 v0, 1.0, v2
	v_rcp_f32_e32 v9, v0
	v_mul_f32_e32 v0, v7, v72
	v_lshl_add_u64 v[4:5], v[20:21], 0, v[52:53]
	v_add_f32_e32 v2, v0, v0
	v_lshl_add_u64 v[4:5], v[4:5], 2, s[42:43]
	v_cmp_ngt_f32_e32 vcc, s9, v2
	s_waitcnt vmcnt(0)
	v_lshlrev_b32_e32 v6, 16, v6
	v_mul_f32_e32 v6, v9, v6
	v_mul_f32_e32 v6, v8, v6
	v_cvt_pk_bf16_f32 v1, v1, v6
	global_store_dword v[4:5], v1, off
	s_and_saveexec_b64 s[2:3], vcc
	s_xor_b64 s[2:3], exec, s[2:3]
	v_fmamk_f32 v1, v2, 0x3ab60b61, v169
	v_fmaak_f32 v1, v2, v1, 0x3d2aaaab
	v_fmaak_f32 v1, v2, v1, 0x3e2aaaab
	v_fma_f32 v1, v2, v1, 0.5
	v_fma_f32 v1, v2, v1, 1.0
	v_mul_f32_e64 v1, v1, -v2
	s_andn2_saveexec_b64 s[2:3], s[2:3]
	v_mul_f32_e32 v1, 0x3fb8aa3b, v2
	v_exp_f32_e32 v1, v1
	s_nop 0
	v_sub_f32_e32 v1, 1.0, v1
	s_or_b64 exec, exec, s[2:3]
	global_load_ushort v4, v[14:15], off offset:32
	v_add_f32_e32 v2, v3, v67
	v_mul_f32_e32 v2, 0xbfb8aa3b, v2
	v_exp_f32_e32 v5, v2
	v_max_f32_e32 v1, v1, v1
	v_max_f32_e32 v1, 0, v1
	v_sqrt_f32_e32 v1, v1
	v_add_f32_e32 v5, 1.0, v5
	v_rcp_f32_e32 v5, v5
	v_lshl_add_u64 v[2:3], v[10:11], 0, v[52:53]
	v_lshl_add_u64 v[2:3], v[2:3], 2, s[42:43]
	s_waitcnt vmcnt(0)
	v_lshlrev_b32_e32 v4, 16, v4
	v_mul_f32_e32 v4, v5, v4
	v_mul_f32_e32 v1, v1, v4
	v_cvt_pk_bf16_f32 v0, v0, v1
	global_store_dword v[2:3], v0, off
	s_mov_b32 s9, 0
